# S5 scans: s_setprio 1 while a wave issues its block of f32 MFMAs, 0 afterwards (timing-only)
# speedup vs baseline: 1.0032x; 1.0032x over previous
; __device__ __forceinline__ void s5_pass1(const Params& p, int layer, int task, char* sm) {
;     ...
; #pragma unroll
;   for (int h = 0; h < 16; h++) { B2[h].x = p.SB[pi * 32 + h]; B2[h].y = p.SB[pi * 32 + 16 + h]; }
;   const float ar = p.SA[pi * 4], ai = p.SA[pi * 4 + 1];
;   float sr = 0.f, si = 0.f;
;   __builtin_amdgcn_wave_barrier();
;   for (int l = 0; l < 128; l++) S5_STEP(sU + l * 16)
.LBB0_477:
	v_mov_b32_e32 v37, v38
	s_nop 1
	v_permlane32_swap_b32_e32 v16, v12
	v_permlane32_swap_b32_e32 v17, v13
	v_permlane32_swap_b32_e32 v18, v14
	v_permlane32_swap_b32_e32 v19, v15
	v_permlane32_swap_b32_e32 v20, v8
	v_permlane32_swap_b32_e32 v21, v9
	v_permlane32_swap_b32_e32 v22, v10
	v_permlane32_swap_b32_e32 v23, v11
	v_permlane32_swap_b32_e32 v24, v4
	v_permlane32_swap_b32_e32 v25, v5
	v_permlane32_swap_b32_e32 v26, v6
	v_permlane32_swap_b32_e32 v27, v7
	v_permlane32_swap_b32_e32 v28, v0
	v_permlane32_swap_b32_e32 v29, v1
	v_permlane32_swap_b32_e32 v30, v2
	v_permlane32_swap_b32_e32 v31, v3
	v_and_b32_e32 v186, 31, v202
	v_lshrrev_b32_e32 v187, 5, v202
	v_lshlrev_b32_e32 v186, 6, v186
	v_lshl_add_u32 v186, v187, 2, v186
	v_add_u32_e32 v186, v41, v186
	ds_read2_b32 v[178:179], v186 offset0:0 offset1:2
	ds_read2_b32 v[180:181], v186 offset0:4 offset1:6
	ds_read2_b32 v[182:183], v186 offset0:8 offset1:10
	ds_read2_b32 v[184:185], v186 offset0:12 offset1:14
	s_waitcnt lgkmcnt(0)
	v_add_u32_e32 v186, 0x800, v186
	s_setprio 1
	v_mfma_f32_32x32x2_f32 v[108:123], v178, v16, 0
	v_mfma_f32_32x32x2_f32 v[124:139], v178, v17, 0
	v_mfma_f32_32x32x2_f32 v[146:161], v178, v12, 0
	v_mfma_f32_32x32x2_f32 v[162:177], v178, v13, 0
	v_mfma_f32_32x32x2_f32 v[108:123], v179, v18, v[108:123]
	v_mfma_f32_32x32x2_f32 v[124:139], v179, v19, v[124:139]
	v_mfma_f32_32x32x2_f32 v[146:161], v179, v14, v[146:161]
	v_mfma_f32_32x32x2_f32 v[162:177], v179, v15, v[162:177]
	v_mfma_f32_32x32x2_f32 v[108:123], v180, v20, v[108:123]
	v_mfma_f32_32x32x2_f32 v[124:139], v180, v21, v[124:139]
	v_mfma_f32_32x32x2_f32 v[146:161], v180, v8, v[146:161]
	v_mfma_f32_32x32x2_f32 v[162:177], v180, v9, v[162:177]
	v_mfma_f32_32x32x2_f32 v[108:123], v181, v22, v[108:123]
	v_mfma_f32_32x32x2_f32 v[124:139], v181, v23, v[124:139]
	v_mfma_f32_32x32x2_f32 v[146:161], v181, v10, v[146:161]
	v_mfma_f32_32x32x2_f32 v[162:177], v181, v11, v[162:177]
	v_mfma_f32_32x32x2_f32 v[108:123], v182, v24, v[108:123]
	v_mfma_f32_32x32x2_f32 v[124:139], v182, v25, v[124:139]
	v_mfma_f32_32x32x2_f32 v[146:161], v182, v4, v[146:161]
	v_mfma_f32_32x32x2_f32 v[162:177], v182, v5, v[162:177]
	v_mfma_f32_32x32x2_f32 v[108:123], v183, v26, v[108:123]
	v_mfma_f32_32x32x2_f32 v[124:139], v183, v27, v[124:139]
	v_mfma_f32_32x32x2_f32 v[146:161], v183, v6, v[146:161]
	v_mfma_f32_32x32x2_f32 v[162:177], v183, v7, v[162:177]
	v_mfma_f32_32x32x2_f32 v[108:123], v184, v28, v[108:123]
	v_mfma_f32_32x32x2_f32 v[124:139], v184, v29, v[124:139]
	v_mfma_f32_32x32x2_f32 v[146:161], v184, v0, v[146:161]
	v_mfma_f32_32x32x2_f32 v[162:177], v184, v1, v[162:177]
	v_mfma_f32_32x32x2_f32 v[108:123], v185, v30, v[108:123]
	v_mfma_f32_32x32x2_f32 v[124:139], v185, v31, v[124:139]
	v_mfma_f32_32x32x2_f32 v[146:161], v185, v2, v[146:161]
	v_mfma_f32_32x32x2_f32 v[162:177], v185, v3, v[162:177]
	s_setprio 0
	s_nop 7
	s_nop 7
	s_nop 7
	v_permlane32_swap_b32_e32 v108, v146
	v_permlane32_swap_b32_e32 v124, v162
	v_permlane32_swap_b32_e32 v109, v147
	v_permlane32_swap_b32_e32 v125, v163
	v_permlane32_swap_b32_e32 v110, v148
	v_permlane32_swap_b32_e32 v126, v164
	v_permlane32_swap_b32_e32 v111, v149
	v_permlane32_swap_b32_e32 v127, v165
	v_permlane32_swap_b32_e32 v112, v150
	v_permlane32_swap_b32_e32 v128, v166
	v_permlane32_swap_b32_e32 v113, v151
	v_permlane32_swap_b32_e32 v129, v167
	v_permlane32_swap_b32_e32 v114, v152
	v_permlane32_swap_b32_e32 v130, v168
	v_permlane32_swap_b32_e32 v115, v153
	v_permlane32_swap_b32_e32 v131, v169
	v_permlane32_swap_b32_e32 v116, v154
	v_permlane32_swap_b32_e32 v132, v170
	v_permlane32_swap_b32_e32 v117, v155
	v_permlane32_swap_b32_e32 v133, v171
	v_permlane32_swap_b32_e32 v118, v156
	v_permlane32_swap_b32_e32 v134, v172
	v_permlane32_swap_b32_e32 v119, v157
	v_permlane32_swap_b32_e32 v135, v173
	v_permlane32_swap_b32_e32 v120, v158
	v_permlane32_swap_b32_e32 v136, v174
	v_permlane32_swap_b32_e32 v121, v159
	v_permlane32_swap_b32_e32 v137, v175
	v_permlane32_swap_b32_e32 v122, v160
	v_permlane32_swap_b32_e32 v138, v176
	v_permlane32_swap_b32_e32 v123, v161
	v_permlane32_swap_b32_e32 v139, v177
	v_mul_f32_e32 v188, v34, v37
	v_mul_f32_e32 v189, v35, v37
	v_fma_f32 v190, v32, v36, -v188
	v_fma_f32 v191, v33, v36, v189
	v_add_f32_e32 v36, v190, v108
	v_add_f32_e32 v37, v191, v124
	v_mul_f32_e32 v188, v34, v37
	v_mul_f32_e32 v189, v35, v37
	v_fma_f32 v190, v32, v36, -v188
	v_fma_f32 v191, v33, v36, v189
	v_add_f32_e32 v36, v190, v109
	v_add_f32_e32 v37, v191, v125
	v_mul_f32_e32 v188, v34, v37
	v_mul_f32_e32 v189, v35, v37
	v_fma_f32 v190, v32, v36, -v188
	v_fma_f32 v191, v33, v36, v189
	v_add_f32_e32 v36, v190, v110
	v_add_f32_e32 v37, v191, v126
	v_mul_f32_e32 v188, v34, v37
	v_mul_f32_e32 v189, v35, v37
	v_fma_f32 v190, v32, v36, -v188
	v_fma_f32 v191, v33, v36, v189
	v_add_f32_e32 v36, v190, v111
	v_add_f32_e32 v37, v191, v127
	v_mul_f32_e32 v188, v34, v37
	v_mul_f32_e32 v189, v35, v37
	v_fma_f32 v190, v32, v36, -v188
	v_fma_f32 v191, v33, v36, v189
	v_add_f32_e32 v36, v190, v146
	v_add_f32_e32 v37, v191, v162
	v_mul_f32_e32 v188, v34, v37
	v_mul_f32_e32 v189, v35, v37
	v_fma_f32 v190, v32, v36, -v188
	v_fma_f32 v191, v33, v36, v189
	v_add_f32_e32 v36, v190, v147
	v_add_f32_e32 v37, v191, v163
	v_mul_f32_e32 v188, v34, v37
	v_mul_f32_e32 v189, v35, v37
	v_fma_f32 v190, v32, v36, -v188
	v_fma_f32 v191, v33, v36, v189
	v_add_f32_e32 v36, v190, v148
	v_add_f32_e32 v37, v191, v164
	v_mul_f32_e32 v188, v34, v37
	v_mul_f32_e32 v189, v35, v37
	v_fma_f32 v190, v32, v36, -v188
	v_fma_f32 v191, v33, v36, v189
	v_add_f32_e32 v36, v190, v149
	v_add_f32_e32 v37, v191, v165
	v_mul_f32_e32 v188, v34, v37
	v_mul_f32_e32 v189, v35, v37
	v_fma_f32 v190, v32, v36, -v188
	v_fma_f32 v191, v33, v36, v189
	v_add_f32_e32 v36, v190, v112
	v_add_f32_e32 v37, v191, v128
	v_mul_f32_e32 v188, v34, v37
	v_mul_f32_e32 v189, v35, v37
	v_fma_f32 v190, v32, v36, -v188
	v_fma_f32 v191, v33, v36, v189
	v_add_f32_e32 v36, v190, v113
	v_add_f32_e32 v37, v191, v129
	v_mul_f32_e32 v188, v34, v37
	v_mul_f32_e32 v189, v35, v37
	v_fma_f32 v190, v32, v36, -v188
	v_fma_f32 v191, v33, v36, v189
	v_add_f32_e32 v36, v190, v114
	v_add_f32_e32 v37, v191, v130
	v_mul_f32_e32 v188, v34, v37
	v_mul_f32_e32 v189, v35, v37
	v_fma_f32 v190, v32, v36, -v188
	v_fma_f32 v191, v33, v36, v189
	v_add_f32_e32 v36, v190, v115
	v_add_f32_e32 v37, v191, v131
	v_mul_f32_e32 v188, v34, v37
	v_mul_f32_e32 v189, v35, v37
	v_fma_f32 v190, v32, v36, -v188
	v_fma_f32 v191, v33, v36, v189
	v_add_f32_e32 v36, v190, v150
	v_add_f32_e32 v37, v191, v166
	v_mul_f32_e32 v188, v34, v37
	v_mul_f32_e32 v189, v35, v37
	v_fma_f32 v190, v32, v36, -v188
	v_fma_f32 v191, v33, v36, v189
	v_add_f32_e32 v36, v190, v151
	v_add_f32_e32 v37, v191, v167
	v_mul_f32_e32 v188, v34, v37
	v_mul_f32_e32 v189, v35, v37
	v_fma_f32 v190, v32, v36, -v188
	v_fma_f32 v191, v33, v36, v189
	v_add_f32_e32 v36, v190, v152
	v_add_f32_e32 v37, v191, v168
	v_mul_f32_e32 v188, v34, v37
	v_mul_f32_e32 v189, v35, v37
	v_fma_f32 v190, v32, v36, -v188
	v_fma_f32 v191, v33, v36, v189
	v_add_f32_e32 v36, v190, v153
	v_add_f32_e32 v37, v191, v169
	v_mul_f32_e32 v188, v34, v37
	v_mul_f32_e32 v189, v35, v37
	v_fma_f32 v190, v32, v36, -v188
	v_fma_f32 v191, v33, v36, v189
	v_add_f32_e32 v36, v190, v116
	v_add_f32_e32 v37, v191, v132
	v_mul_f32_e32 v188, v34, v37
	v_mul_f32_e32 v189, v35, v37
	v_fma_f32 v190, v32, v36, -v188
	v_fma_f32 v191, v33, v36, v189
	v_add_f32_e32 v36, v190, v117
	v_add_f32_e32 v37, v191, v133
	v_mul_f32_e32 v188, v34, v37
	v_mul_f32_e32 v189, v35, v37
	v_fma_f32 v190, v32, v36, -v188
	v_fma_f32 v191, v33, v36, v189
	v_add_f32_e32 v36, v190, v118
	v_add_f32_e32 v37, v191, v134
	v_mul_f32_e32 v188, v34, v37
	v_mul_f32_e32 v189, v35, v37
	v_fma_f32 v190, v32, v36, -v188
	v_fma_f32 v191, v33, v36, v189
	v_add_f32_e32 v36, v190, v119
	v_add_f32_e32 v37, v191, v135
	v_mul_f32_e32 v188, v34, v37
	v_mul_f32_e32 v189, v35, v37
	v_fma_f32 v190, v32, v36, -v188
	v_fma_f32 v191, v33, v36, v189
	v_add_f32_e32 v36, v190, v154
	v_add_f32_e32 v37, v191, v170
	v_mul_f32_e32 v188, v34, v37
	v_mul_f32_e32 v189, v35, v37
	v_fma_f32 v190, v32, v36, -v188
	v_fma_f32 v191, v33, v36, v189
	v_add_f32_e32 v36, v190, v155
	v_add_f32_e32 v37, v191, v171
	v_mul_f32_e32 v188, v34, v37
	v_mul_f32_e32 v189, v35, v37
	v_fma_f32 v190, v32, v36, -v188
	v_fma_f32 v191, v33, v36, v189
	v_add_f32_e32 v36, v190, v156
	v_add_f32_e32 v37, v191, v172
	v_mul_f32_e32 v188, v34, v37
	v_mul_f32_e32 v189, v35, v37
	v_fma_f32 v190, v32, v36, -v188
	v_fma_f32 v191, v33, v36, v189
	v_add_f32_e32 v36, v190, v157
	v_add_f32_e32 v37, v191, v173
	v_mul_f32_e32 v188, v34, v37
	v_mul_f32_e32 v189, v35, v37
	v_fma_f32 v190, v32, v36, -v188
	v_fma_f32 v191, v33, v36, v189
	v_add_f32_e32 v36, v190, v120
	v_add_f32_e32 v37, v191, v136
	v_mul_f32_e32 v188, v34, v37
	v_mul_f32_e32 v189, v35, v37
	v_fma_f32 v190, v32, v36, -v188
	v_fma_f32 v191, v33, v36, v189
	v_add_f32_e32 v36, v190, v121
	v_add_f32_e32 v37, v191, v137
	v_mul_f32_e32 v188, v34, v37
	v_mul_f32_e32 v189, v35, v37
	v_fma_f32 v190, v32, v36, -v188
	v_fma_f32 v191, v33, v36, v189
	v_add_f32_e32 v36, v190, v122
	v_add_f32_e32 v37, v191, v138
	v_mul_f32_e32 v188, v34, v37
	v_mul_f32_e32 v189, v35, v37
	v_fma_f32 v190, v32, v36, -v188
	v_fma_f32 v191, v33, v36, v189
	v_add_f32_e32 v36, v190, v123
	v_add_f32_e32 v37, v191, v139
	v_mul_f32_e32 v188, v34, v37
	v_mul_f32_e32 v189, v35, v37
	v_fma_f32 v190, v32, v36, -v188
	v_fma_f32 v191, v33, v36, v189
	v_add_f32_e32 v36, v190, v158
	v_add_f32_e32 v37, v191, v174
	v_mul_f32_e32 v188, v34, v37
	v_mul_f32_e32 v189, v35, v37
	v_fma_f32 v190, v32, v36, -v188
	v_fma_f32 v191, v33, v36, v189
	v_add_f32_e32 v36, v190, v159
	v_add_f32_e32 v37, v191, v175
	v_mul_f32_e32 v188, v34, v37
	v_mul_f32_e32 v189, v35, v37
	v_fma_f32 v190, v32, v36, -v188
	v_fma_f32 v191, v33, v36, v189
	v_add_f32_e32 v36, v190, v160
	v_add_f32_e32 v37, v191, v176
	v_mul_f32_e32 v188, v34, v37
	v_mul_f32_e32 v189, v35, v37
	v_fma_f32 v190, v32, v36, -v188
	v_fma_f32 v191, v33, v36, v189
	v_add_f32_e32 v36, v190, v161
	v_add_f32_e32 v37, v191, v177
	ds_read2_b32 v[178:179], v186 offset0:0 offset1:2
	ds_read2_b32 v[180:181], v186 offset0:4 offset1:6
	ds_read2_b32 v[182:183], v186 offset0:8 offset1:10
	ds_read2_b32 v[184:185], v186 offset0:12 offset1:14
	s_waitcnt lgkmcnt(0)
	v_add_u32_e32 v186, 0x800, v186
	s_setprio 1
	v_mfma_f32_32x32x2_f32 v[108:123], v178, v16, 0
	v_mfma_f32_32x32x2_f32 v[124:139], v178, v17, 0
	v_mfma_f32_32x32x2_f32 v[146:161], v178, v12, 0
	v_mfma_f32_32x32x2_f32 v[162:177], v178, v13, 0
	v_mfma_f32_32x32x2_f32 v[108:123], v179, v18, v[108:123]
	v_mfma_f32_32x32x2_f32 v[124:139], v179, v19, v[124:139]
	v_mfma_f32_32x32x2_f32 v[146:161], v179, v14, v[146:161]
	v_mfma_f32_32x32x2_f32 v[162:177], v179, v15, v[162:177]
	v_mfma_f32_32x32x2_f32 v[108:123], v180, v20, v[108:123]
	v_mfma_f32_32x32x2_f32 v[124:139], v180, v21, v[124:139]
	v_mfma_f32_32x32x2_f32 v[146:161], v180, v8, v[146:161]
	v_mfma_f32_32x32x2_f32 v[162:177], v180, v9, v[162:177]
	v_mfma_f32_32x32x2_f32 v[108:123], v181, v22, v[108:123]
	v_mfma_f32_32x32x2_f32 v[124:139], v181, v23, v[124:139]
	v_mfma_f32_32x32x2_f32 v[146:161], v181, v10, v[146:161]
	v_mfma_f32_32x32x2_f32 v[162:177], v181, v11, v[162:177]
	v_mfma_f32_32x32x2_f32 v[108:123], v182, v24, v[108:123]
	v_mfma_f32_32x32x2_f32 v[124:139], v182, v25, v[124:139]
	v_mfma_f32_32x32x2_f32 v[146:161], v182, v4, v[146:161]
	v_mfma_f32_32x32x2_f32 v[162:177], v182, v5, v[162:177]
	v_mfma_f32_32x32x2_f32 v[108:123], v183, v26, v[108:123]
	v_mfma_f32_32x32x2_f32 v[124:139], v183, v27, v[124:139]
	v_mfma_f32_32x32x2_f32 v[146:161], v183, v6, v[146:161]
	v_mfma_f32_32x32x2_f32 v[162:177], v183, v7, v[162:177]
	v_mfma_f32_32x32x2_f32 v[108:123], v184, v28, v[108:123]
	v_mfma_f32_32x32x2_f32 v[124:139], v184, v29, v[124:139]
	v_mfma_f32_32x32x2_f32 v[146:161], v184, v0, v[146:161]
	v_mfma_f32_32x32x2_f32 v[162:177], v184, v1, v[162:177]
	v_mfma_f32_32x32x2_f32 v[108:123], v185, v30, v[108:123]
	v_mfma_f32_32x32x2_f32 v[124:139], v185, v31, v[124:139]
	v_mfma_f32_32x32x2_f32 v[146:161], v185, v2, v[146:161]
	v_mfma_f32_32x32x2_f32 v[162:177], v185, v3, v[162:177]
	s_setprio 0
	s_nop 7
	s_nop 7
	s_nop 7
	v_permlane32_swap_b32_e32 v108, v146
	v_permlane32_swap_b32_e32 v124, v162
	v_permlane32_swap_b32_e32 v109, v147
	v_permlane32_swap_b32_e32 v125, v163
	v_permlane32_swap_b32_e32 v110, v148
	v_permlane32_swap_b32_e32 v126, v164
	v_permlane32_swap_b32_e32 v111, v149
	v_permlane32_swap_b32_e32 v127, v165
	v_permlane32_swap_b32_e32 v112, v150
	v_permlane32_swap_b32_e32 v128, v166
	v_permlane32_swap_b32_e32 v113, v151
	v_permlane32_swap_b32_e32 v129, v167
	v_permlane32_swap_b32_e32 v114, v152
	v_permlane32_swap_b32_e32 v130, v168
	v_permlane32_swap_b32_e32 v115, v153
	v_permlane32_swap_b32_e32 v131, v169
	v_permlane32_swap_b32_e32 v116, v154
	v_permlane32_swap_b32_e32 v132, v170
	v_permlane32_swap_b32_e32 v117, v155
	v_permlane32_swap_b32_e32 v133, v171
	v_permlane32_swap_b32_e32 v118, v156
	v_permlane32_swap_b32_e32 v134, v172
	v_permlane32_swap_b32_e32 v119, v157
	v_permlane32_swap_b32_e32 v135, v173
	v_permlane32_swap_b32_e32 v120, v158
	v_permlane32_swap_b32_e32 v136, v174
	v_permlane32_swap_b32_e32 v121, v159
	v_permlane32_swap_b32_e32 v137, v175
	v_permlane32_swap_b32_e32 v122, v160
	v_permlane32_swap_b32_e32 v138, v176
	v_permlane32_swap_b32_e32 v123, v161
	v_permlane32_swap_b32_e32 v139, v177
	v_mul_f32_e32 v188, v34, v37
	v_mul_f32_e32 v189, v35, v37
	v_fma_f32 v190, v32, v36, -v188
	v_fma_f32 v191, v33, v36, v189
	v_add_f32_e32 v36, v190, v108
	v_add_f32_e32 v37, v191, v124
	v_mul_f32_e32 v188, v34, v37
	v_mul_f32_e32 v189, v35, v37
	v_fma_f32 v190, v32, v36, -v188
	v_fma_f32 v191, v33, v36, v189
	v_add_f32_e32 v36, v190, v109
	v_add_f32_e32 v37, v191, v125
	v_mul_f32_e32 v188, v34, v37
	v_mul_f32_e32 v189, v35, v37
	v_fma_f32 v190, v32, v36, -v188
	v_fma_f32 v191, v33, v36, v189
	v_add_f32_e32 v36, v190, v110
	v_add_f32_e32 v37, v191, v126
	v_mul_f32_e32 v188, v34, v37
	v_mul_f32_e32 v189, v35, v37
	v_fma_f32 v190, v32, v36, -v188
	v_fma_f32 v191, v33, v36, v189
	v_add_f32_e32 v36, v190, v111
	v_add_f32_e32 v37, v191, v127
	v_mul_f32_e32 v188, v34, v37
	v_mul_f32_e32 v189, v35, v37
	v_fma_f32 v190, v32, v36, -v188
	v_fma_f32 v191, v33, v36, v189
	v_add_f32_e32 v36, v190, v146
	v_add_f32_e32 v37, v191, v162
	v_mul_f32_e32 v188, v34, v37
	v_mul_f32_e32 v189, v35, v37
	v_fma_f32 v190, v32, v36, -v188
	v_fma_f32 v191, v33, v36, v189
	v_add_f32_e32 v36, v190, v147
	v_add_f32_e32 v37, v191, v163
	v_mul_f32_e32 v188, v34, v37
	v_mul_f32_e32 v189, v35, v37
	v_fma_f32 v190, v32, v36, -v188
	v_fma_f32 v191, v33, v36, v189
	v_add_f32_e32 v36, v190, v148
	v_add_f32_e32 v37, v191, v164
	v_mul_f32_e32 v188, v34, v37
	v_mul_f32_e32 v189, v35, v37
	v_fma_f32 v190, v32, v36, -v188
	v_fma_f32 v191, v33, v36, v189
	v_add_f32_e32 v36, v190, v149
	v_add_f32_e32 v37, v191, v165
	v_mul_f32_e32 v188, v34, v37
	v_mul_f32_e32 v189, v35, v37
	v_fma_f32 v190, v32, v36, -v188
	v_fma_f32 v191, v33, v36, v189
	v_add_f32_e32 v36, v190, v112
	v_add_f32_e32 v37, v191, v128
	v_mul_f32_e32 v188, v34, v37
	v_mul_f32_e32 v189, v35, v37
	v_fma_f32 v190, v32, v36, -v188
	v_fma_f32 v191, v33, v36, v189
	v_add_f32_e32 v36, v190, v113
	v_add_f32_e32 v37, v191, v129
	v_mul_f32_e32 v188, v34, v37
	v_mul_f32_e32 v189, v35, v37
	v_fma_f32 v190, v32, v36, -v188
	v_fma_f32 v191, v33, v36, v189
	v_add_f32_e32 v36, v190, v114
	v_add_f32_e32 v37, v191, v130
	v_mul_f32_e32 v188, v34, v37
	v_mul_f32_e32 v189, v35, v37
	v_fma_f32 v190, v32, v36, -v188
	v_fma_f32 v191, v33, v36, v189
	v_add_f32_e32 v36, v190, v115
	v_add_f32_e32 v37, v191, v131
	v_mul_f32_e32 v188, v34, v37
	v_mul_f32_e32 v189, v35, v37
	v_fma_f32 v190, v32, v36, -v188
	v_fma_f32 v191, v33, v36, v189
	v_add_f32_e32 v36, v190, v150
	v_add_f32_e32 v37, v191, v166
	v_mul_f32_e32 v188, v34, v37
	v_mul_f32_e32 v189, v35, v37
	v_fma_f32 v190, v32, v36, -v188
	v_fma_f32 v191, v33, v36, v189
	v_add_f32_e32 v36, v190, v151
	v_add_f32_e32 v37, v191, v167
	v_mul_f32_e32 v188, v34, v37
	v_mul_f32_e32 v189, v35, v37
	v_fma_f32 v190, v32, v36, -v188
	v_fma_f32 v191, v33, v36, v189
	v_add_f32_e32 v36, v190, v152
	v_add_f32_e32 v37, v191, v168
	v_mul_f32_e32 v188, v34, v37
	v_mul_f32_e32 v189, v35, v37
	v_fma_f32 v190, v32, v36, -v188
	v_fma_f32 v191, v33, v36, v189
	v_add_f32_e32 v36, v190, v153
	v_add_f32_e32 v37, v191, v169
	v_mul_f32_e32 v188, v34, v37
	v_mul_f32_e32 v189, v35, v37
	v_fma_f32 v190, v32, v36, -v188
	v_fma_f32 v191, v33, v36, v189
	v_add_f32_e32 v36, v190, v116
	v_add_f32_e32 v37, v191, v132
	v_mul_f32_e32 v188, v34, v37
	v_mul_f32_e32 v189, v35, v37
	v_fma_f32 v190, v32, v36, -v188
	v_fma_f32 v191, v33, v36, v189
	v_add_f32_e32 v36, v190, v117
	v_add_f32_e32 v37, v191, v133
	v_mul_f32_e32 v188, v34, v37
	v_mul_f32_e32 v189, v35, v37
	v_fma_f32 v190, v32, v36, -v188
	v_fma_f32 v191, v33, v36, v189
	v_add_f32_e32 v36, v190, v118
	v_add_f32_e32 v37, v191, v134
	v_mul_f32_e32 v188, v34, v37
	v_mul_f32_e32 v189, v35, v37
	v_fma_f32 v190, v32, v36, -v188
	v_fma_f32 v191, v33, v36, v189
	v_add_f32_e32 v36, v190, v119
	v_add_f32_e32 v37, v191, v135
	v_mul_f32_e32 v188, v34, v37
	v_mul_f32_e32 v189, v35, v37
	v_fma_f32 v190, v32, v36, -v188
	v_fma_f32 v191, v33, v36, v189
	v_add_f32_e32 v36, v190, v154
	v_add_f32_e32 v37, v191, v170
	v_mul_f32_e32 v188, v34, v37
	v_mul_f32_e32 v189, v35, v37
	v_fma_f32 v190, v32, v36, -v188
	v_fma_f32 v191, v33, v36, v189
	v_add_f32_e32 v36, v190, v155
	v_add_f32_e32 v37, v191, v171
	v_mul_f32_e32 v188, v34, v37
	v_mul_f32_e32 v189, v35, v37
	v_fma_f32 v190, v32, v36, -v188
	v_fma_f32 v191, v33, v36, v189
	v_add_f32_e32 v36, v190, v156
	v_add_f32_e32 v37, v191, v172
	v_mul_f32_e32 v188, v34, v37
	v_mul_f32_e32 v189, v35, v37
	v_fma_f32 v190, v32, v36, -v188
	v_fma_f32 v191, v33, v36, v189
	v_add_f32_e32 v36, v190, v157
	v_add_f32_e32 v37, v191, v173
	v_mul_f32_e32 v188, v34, v37
	v_mul_f32_e32 v189, v35, v37
	v_fma_f32 v190, v32, v36, -v188
	v_fma_f32 v191, v33, v36, v189
	v_add_f32_e32 v36, v190, v120
	v_add_f32_e32 v37, v191, v136
	v_mul_f32_e32 v188, v34, v37
	v_mul_f32_e32 v189, v35, v37
	v_fma_f32 v190, v32, v36, -v188
	v_fma_f32 v191, v33, v36, v189
	v_add_f32_e32 v36, v190, v121
	v_add_f32_e32 v37, v191, v137
	v_mul_f32_e32 v188, v34, v37
	v_mul_f32_e32 v189, v35, v37
	v_fma_f32 v190, v32, v36, -v188
	v_fma_f32 v191, v33, v36, v189
	v_add_f32_e32 v36, v190, v122
	v_add_f32_e32 v37, v191, v138
	v_mul_f32_e32 v188, v34, v37
	v_mul_f32_e32 v189, v35, v37
	v_fma_f32 v190, v32, v36, -v188
	v_fma_f32 v191, v33, v36, v189
	v_add_f32_e32 v36, v190, v123
	v_add_f32_e32 v37, v191, v139
	v_mul_f32_e32 v188, v34, v37
	v_mul_f32_e32 v189, v35, v37
	v_fma_f32 v190, v32, v36, -v188
	v_fma_f32 v191, v33, v36, v189
	v_add_f32_e32 v36, v190, v158
	v_add_f32_e32 v37, v191, v174
	v_mul_f32_e32 v188, v34, v37
	v_mul_f32_e32 v189, v35, v37
	v_fma_f32 v190, v32, v36, -v188
	v_fma_f32 v191, v33, v36, v189
	v_add_f32_e32 v36, v190, v159
	v_add_f32_e32 v37, v191, v175
	v_mul_f32_e32 v188, v34, v37
	v_mul_f32_e32 v189, v35, v37
	v_fma_f32 v190, v32, v36, -v188
	v_fma_f32 v191, v33, v36, v189
	v_add_f32_e32 v36, v190, v160
	v_add_f32_e32 v37, v191, v176
	v_mul_f32_e32 v188, v34, v37
	v_mul_f32_e32 v189, v35, v37
	v_fma_f32 v190, v32, v36, -v188
	v_fma_f32 v191, v33, v36, v189
	v_add_f32_e32 v36, v190, v161
	v_add_f32_e32 v37, v191, v177
	ds_read2_b32 v[178:179], v186 offset0:0 offset1:2
	ds_read2_b32 v[180:181], v186 offset0:4 offset1:6
	ds_read2_b32 v[182:183], v186 offset0:8 offset1:10
	ds_read2_b32 v[184:185], v186 offset0:12 offset1:14
	s_waitcnt lgkmcnt(0)
	v_add_u32_e32 v186, 0x800, v186
	s_setprio 1
	v_mfma_f32_32x32x2_f32 v[108:123], v178, v16, 0
	v_mfma_f32_32x32x2_f32 v[124:139], v178, v17, 0
	v_mfma_f32_32x32x2_f32 v[146:161], v178, v12, 0
	v_mfma_f32_32x32x2_f32 v[162:177], v178, v13, 0
	v_mfma_f32_32x32x2_f32 v[108:123], v179, v18, v[108:123]
	v_mfma_f32_32x32x2_f32 v[124:139], v179, v19, v[124:139]
	v_mfma_f32_32x32x2_f32 v[146:161], v179, v14, v[146:161]
	v_mfma_f32_32x32x2_f32 v[162:177], v179, v15, v[162:177]
	v_mfma_f32_32x32x2_f32 v[108:123], v180, v20, v[108:123]
	v_mfma_f32_32x32x2_f32 v[124:139], v180, v21, v[124:139]
	v_mfma_f32_32x32x2_f32 v[146:161], v180, v8, v[146:161]
	v_mfma_f32_32x32x2_f32 v[162:177], v180, v9, v[162:177]
	v_mfma_f32_32x32x2_f32 v[108:123], v181, v22, v[108:123]
	v_mfma_f32_32x32x2_f32 v[124:139], v181, v23, v[124:139]
	v_mfma_f32_32x32x2_f32 v[146:161], v181, v10, v[146:161]
	v_mfma_f32_32x32x2_f32 v[162:177], v181, v11, v[162:177]
	v_mfma_f32_32x32x2_f32 v[108:123], v182, v24, v[108:123]
	v_mfma_f32_32x32x2_f32 v[124:139], v182, v25, v[124:139]
	v_mfma_f32_32x32x2_f32 v[146:161], v182, v4, v[146:161]
	v_mfma_f32_32x32x2_f32 v[162:177], v182, v5, v[162:177]
	v_mfma_f32_32x32x2_f32 v[108:123], v183, v26, v[108:123]
	v_mfma_f32_32x32x2_f32 v[124:139], v183, v27, v[124:139]
	v_mfma_f32_32x32x2_f32 v[146:161], v183, v6, v[146:161]
	v_mfma_f32_32x32x2_f32 v[162:177], v183, v7, v[162:177]
	v_mfma_f32_32x32x2_f32 v[108:123], v184, v28, v[108:123]
	v_mfma_f32_32x32x2_f32 v[124:139], v184, v29, v[124:139]
	v_mfma_f32_32x32x2_f32 v[146:161], v184, v0, v[146:161]
	v_mfma_f32_32x32x2_f32 v[162:177], v184, v1, v[162:177]
	v_mfma_f32_32x32x2_f32 v[108:123], v185, v30, v[108:123]
	v_mfma_f32_32x32x2_f32 v[124:139], v185, v31, v[124:139]
	v_mfma_f32_32x32x2_f32 v[146:161], v185, v2, v[146:161]
	v_mfma_f32_32x32x2_f32 v[162:177], v185, v3, v[162:177]
	s_setprio 0
	s_nop 7
	s_nop 7
	s_nop 7
	v_permlane32_swap_b32_e32 v108, v146
	v_permlane32_swap_b32_e32 v124, v162
	v_permlane32_swap_b32_e32 v109, v147
	v_permlane32_swap_b32_e32 v125, v163
	v_permlane32_swap_b32_e32 v110, v148
	v_permlane32_swap_b32_e32 v126, v164
	v_permlane32_swap_b32_e32 v111, v149
	v_permlane32_swap_b32_e32 v127, v165
	v_permlane32_swap_b32_e32 v112, v150
	v_permlane32_swap_b32_e32 v128, v166
	v_permlane32_swap_b32_e32 v113, v151
	v_permlane32_swap_b32_e32 v129, v167
	v_permlane32_swap_b32_e32 v114, v152
	v_permlane32_swap_b32_e32 v130, v168
	v_permlane32_swap_b32_e32 v115, v153
	v_permlane32_swap_b32_e32 v131, v169
	v_permlane32_swap_b32_e32 v116, v154
	v_permlane32_swap_b32_e32 v132, v170
	v_permlane32_swap_b32_e32 v117, v155
	v_permlane32_swap_b32_e32 v133, v171
	v_permlane32_swap_b32_e32 v118, v156
	v_permlane32_swap_b32_e32 v134, v172
	v_permlane32_swap_b32_e32 v119, v157
	v_permlane32_swap_b32_e32 v135, v173
	v_permlane32_swap_b32_e32 v120, v158
	v_permlane32_swap_b32_e32 v136, v174
	v_permlane32_swap_b32_e32 v121, v159
	v_permlane32_swap_b32_e32 v137, v175
	v_permlane32_swap_b32_e32 v122, v160
	v_permlane32_swap_b32_e32 v138, v176
	v_permlane32_swap_b32_e32 v123, v161
	v_permlane32_swap_b32_e32 v139, v177
	v_mul_f32_e32 v188, v34, v37
	v_mul_f32_e32 v189, v35, v37
	v_fma_f32 v190, v32, v36, -v188
	v_fma_f32 v191, v33, v36, v189
	v_add_f32_e32 v36, v190, v108
	v_add_f32_e32 v37, v191, v124
	v_mul_f32_e32 v188, v34, v37
	v_mul_f32_e32 v189, v35, v37
	v_fma_f32 v190, v32, v36, -v188
	v_fma_f32 v191, v33, v36, v189
	v_add_f32_e32 v36, v190, v109
	v_add_f32_e32 v37, v191, v125
	v_mul_f32_e32 v188, v34, v37
	v_mul_f32_e32 v189, v35, v37
	v_fma_f32 v190, v32, v36, -v188
	v_fma_f32 v191, v33, v36, v189
	v_add_f32_e32 v36, v190, v110
	v_add_f32_e32 v37, v191, v126
	v_mul_f32_e32 v188, v34, v37
	v_mul_f32_e32 v189, v35, v37
	v_fma_f32 v190, v32, v36, -v188
	v_fma_f32 v191, v33, v36, v189
	v_add_f32_e32 v36, v190, v111
	v_add_f32_e32 v37, v191, v127
	v_mul_f32_e32 v188, v34, v37
	v_mul_f32_e32 v189, v35, v37
	v_fma_f32 v190, v32, v36, -v188
	v_fma_f32 v191, v33, v36, v189
	v_add_f32_e32 v36, v190, v146
	v_add_f32_e32 v37, v191, v162
	v_mul_f32_e32 v188, v34, v37
	v_mul_f32_e32 v189, v35, v37
	v_fma_f32 v190, v32, v36, -v188
	v_fma_f32 v191, v33, v36, v189
	v_add_f32_e32 v36, v190, v147
	v_add_f32_e32 v37, v191, v163
	v_mul_f32_e32 v188, v34, v37
	v_mul_f32_e32 v189, v35, v37
	v_fma_f32 v190, v32, v36, -v188
	v_fma_f32 v191, v33, v36, v189
	v_add_f32_e32 v36, v190, v148
	v_add_f32_e32 v37, v191, v164
	v_mul_f32_e32 v188, v34, v37
	v_mul_f32_e32 v189, v35, v37
	v_fma_f32 v190, v32, v36, -v188
	v_fma_f32 v191, v33, v36, v189
	v_add_f32_e32 v36, v190, v149
	v_add_f32_e32 v37, v191, v165
	v_mul_f32_e32 v188, v34, v37
	v_mul_f32_e32 v189, v35, v37
	v_fma_f32 v190, v32, v36, -v188
	v_fma_f32 v191, v33, v36, v189
	v_add_f32_e32 v36, v190, v112
	v_add_f32_e32 v37, v191, v128
	v_mul_f32_e32 v188, v34, v37
	v_mul_f32_e32 v189, v35, v37
	v_fma_f32 v190, v32, v36, -v188
	v_fma_f32 v191, v33, v36, v189
	v_add_f32_e32 v36, v190, v113
	v_add_f32_e32 v37, v191, v129
	v_mul_f32_e32 v188, v34, v37
	v_mul_f32_e32 v189, v35, v37
	v_fma_f32 v190, v32, v36, -v188
	v_fma_f32 v191, v33, v36, v189
	v_add_f32_e32 v36, v190, v114
	v_add_f32_e32 v37, v191, v130
	v_mul_f32_e32 v188, v34, v37
	v_mul_f32_e32 v189, v35, v37
	v_fma_f32 v190, v32, v36, -v188
	v_fma_f32 v191, v33, v36, v189
	v_add_f32_e32 v36, v190, v115
	v_add_f32_e32 v37, v191, v131
	v_mul_f32_e32 v188, v34, v37
	v_mul_f32_e32 v189, v35, v37
	v_fma_f32 v190, v32, v36, -v188
	v_fma_f32 v191, v33, v36, v189
	v_add_f32_e32 v36, v190, v150
	v_add_f32_e32 v37, v191, v166
	v_mul_f32_e32 v188, v34, v37
	v_mul_f32_e32 v189, v35, v37
	v_fma_f32 v190, v32, v36, -v188
	v_fma_f32 v191, v33, v36, v189
	v_add_f32_e32 v36, v190, v151
	v_add_f32_e32 v37, v191, v167
	v_mul_f32_e32 v188, v34, v37
	v_mul_f32_e32 v189, v35, v37
	v_fma_f32 v190, v32, v36, -v188
	v_fma_f32 v191, v33, v36, v189
	v_add_f32_e32 v36, v190, v152
	v_add_f32_e32 v37, v191, v168
	v_mul_f32_e32 v188, v34, v37
	v_mul_f32_e32 v189, v35, v37
	v_fma_f32 v190, v32, v36, -v188
	v_fma_f32 v191, v33, v36, v189
	v_add_f32_e32 v36, v190, v153
	v_add_f32_e32 v37, v191, v169
	v_mul_f32_e32 v188, v34, v37
	v_mul_f32_e32 v189, v35, v37
	v_fma_f32 v190, v32, v36, -v188
	v_fma_f32 v191, v33, v36, v189
	v_add_f32_e32 v36, v190, v116
	v_add_f32_e32 v37, v191, v132
	v_mul_f32_e32 v188, v34, v37
	v_mul_f32_e32 v189, v35, v37
	v_fma_f32 v190, v32, v36, -v188
	v_fma_f32 v191, v33, v36, v189
	v_add_f32_e32 v36, v190, v117
	v_add_f32_e32 v37, v191, v133
	v_mul_f32_e32 v188, v34, v37
	v_mul_f32_e32 v189, v35, v37
	v_fma_f32 v190, v32, v36, -v188
	v_fma_f32 v191, v33, v36, v189
	v_add_f32_e32 v36, v190, v118
	v_add_f32_e32 v37, v191, v134
	v_mul_f32_e32 v188, v34, v37
	v_mul_f32_e32 v189, v35, v37
	v_fma_f32 v190, v32, v36, -v188
	v_fma_f32 v191, v33, v36, v189
	v_add_f32_e32 v36, v190, v119
	v_add_f32_e32 v37, v191, v135
	v_mul_f32_e32 v188, v34, v37
	v_mul_f32_e32 v189, v35, v37
	v_fma_f32 v190, v32, v36, -v188
	v_fma_f32 v191, v33, v36, v189
	v_add_f32_e32 v36, v190, v154
	v_add_f32_e32 v37, v191, v170
	v_mul_f32_e32 v188, v34, v37
	v_mul_f32_e32 v189, v35, v37
	v_fma_f32 v190, v32, v36, -v188
	v_fma_f32 v191, v33, v36, v189
	v_add_f32_e32 v36, v190, v155
	v_add_f32_e32 v37, v191, v171
	v_mul_f32_e32 v188, v34, v37
	v_mul_f32_e32 v189, v35, v37
	v_fma_f32 v190, v32, v36, -v188
	v_fma_f32 v191, v33, v36, v189
	v_add_f32_e32 v36, v190, v156
	v_add_f32_e32 v37, v191, v172
	v_mul_f32_e32 v188, v34, v37
	v_mul_f32_e32 v189, v35, v37
	v_fma_f32 v190, v32, v36, -v188
	v_fma_f32 v191, v33, v36, v189
	v_add_f32_e32 v36, v190, v157
	v_add_f32_e32 v37, v191, v173
	v_mul_f32_e32 v188, v34, v37
	v_mul_f32_e32 v189, v35, v37
	v_fma_f32 v190, v32, v36, -v188
	v_fma_f32 v191, v33, v36, v189
	v_add_f32_e32 v36, v190, v120
	v_add_f32_e32 v37, v191, v136
	v_mul_f32_e32 v188, v34, v37
	v_mul_f32_e32 v189, v35, v37
	v_fma_f32 v190, v32, v36, -v188
	v_fma_f32 v191, v33, v36, v189
	v_add_f32_e32 v36, v190, v121
	v_add_f32_e32 v37, v191, v137
	v_mul_f32_e32 v188, v34, v37
	v_mul_f32_e32 v189, v35, v37
	v_fma_f32 v190, v32, v36, -v188
	v_fma_f32 v191, v33, v36, v189
	v_add_f32_e32 v36, v190, v122
	v_add_f32_e32 v37, v191, v138
	v_mul_f32_e32 v188, v34, v37
	v_mul_f32_e32 v189, v35, v37
	v_fma_f32 v190, v32, v36, -v188
	v_fma_f32 v191, v33, v36, v189
	v_add_f32_e32 v36, v190, v123
	v_add_f32_e32 v37, v191, v139
	v_mul_f32_e32 v188, v34, v37
	v_mul_f32_e32 v189, v35, v37
	v_fma_f32 v190, v32, v36, -v188
	v_fma_f32 v191, v33, v36, v189
	v_add_f32_e32 v36, v190, v158
	v_add_f32_e32 v37, v191, v174
	v_mul_f32_e32 v188, v34, v37
	v_mul_f32_e32 v189, v35, v37
	v_fma_f32 v190, v32, v36, -v188
	v_fma_f32 v191, v33, v36, v189
	v_add_f32_e32 v36, v190, v159
	v_add_f32_e32 v37, v191, v175
	v_mul_f32_e32 v188, v34, v37
	v_mul_f32_e32 v189, v35, v37
	v_fma_f32 v190, v32, v36, -v188
	v_fma_f32 v191, v33, v36, v189
	v_add_f32_e32 v36, v190, v160
	v_add_f32_e32 v37, v191, v176
	v_mul_f32_e32 v188, v34, v37
	v_mul_f32_e32 v189, v35, v37
	v_fma_f32 v190, v32, v36, -v188
	v_fma_f32 v191, v33, v36, v189
	v_add_f32_e32 v36, v190, v161
	v_add_f32_e32 v37, v191, v177
	ds_read2_b32 v[178:179], v186 offset0:0 offset1:2
	ds_read2_b32 v[180:181], v186 offset0:4 offset1:6
	ds_read2_b32 v[182:183], v186 offset0:8 offset1:10
	ds_read2_b32 v[184:185], v186 offset0:12 offset1:14
	s_waitcnt lgkmcnt(0)
	s_setprio 1
	v_mfma_f32_32x32x2_f32 v[108:123], v178, v16, 0
	v_mfma_f32_32x32x2_f32 v[124:139], v178, v17, 0
	v_mfma_f32_32x32x2_f32 v[146:161], v178, v12, 0
	v_mfma_f32_32x32x2_f32 v[162:177], v178, v13, 0
	v_mfma_f32_32x32x2_f32 v[108:123], v179, v18, v[108:123]
	v_mfma_f32_32x32x2_f32 v[124:139], v179, v19, v[124:139]
	v_mfma_f32_32x32x2_f32 v[146:161], v179, v14, v[146:161]
	v_mfma_f32_32x32x2_f32 v[162:177], v179, v15, v[162:177]
	v_mfma_f32_32x32x2_f32 v[108:123], v180, v20, v[108:123]
	v_mfma_f32_32x32x2_f32 v[124:139], v180, v21, v[124:139]
	v_mfma_f32_32x32x2_f32 v[146:161], v180, v8, v[146:161]
	v_mfma_f32_32x32x2_f32 v[162:177], v180, v9, v[162:177]
	v_mfma_f32_32x32x2_f32 v[108:123], v181, v22, v[108:123]
	v_mfma_f32_32x32x2_f32 v[124:139], v181, v23, v[124:139]
	v_mfma_f32_32x32x2_f32 v[146:161], v181, v10, v[146:161]
	v_mfma_f32_32x32x2_f32 v[162:177], v181, v11, v[162:177]
	v_mfma_f32_32x32x2_f32 v[108:123], v182, v24, v[108:123]
	v_mfma_f32_32x32x2_f32 v[124:139], v182, v25, v[124:139]
	v_mfma_f32_32x32x2_f32 v[146:161], v182, v4, v[146:161]
	v_mfma_f32_32x32x2_f32 v[162:177], v182, v5, v[162:177]
	v_mfma_f32_32x32x2_f32 v[108:123], v183, v26, v[108:123]
	v_mfma_f32_32x32x2_f32 v[124:139], v183, v27, v[124:139]
	v_mfma_f32_32x32x2_f32 v[146:161], v183, v6, v[146:161]
	v_mfma_f32_32x32x2_f32 v[162:177], v183, v7, v[162:177]
	v_mfma_f32_32x32x2_f32 v[108:123], v184, v28, v[108:123]
	v_mfma_f32_32x32x2_f32 v[124:139], v184, v29, v[124:139]
	v_mfma_f32_32x32x2_f32 v[146:161], v184, v0, v[146:161]
	v_mfma_f32_32x32x2_f32 v[162:177], v184, v1, v[162:177]
	v_mfma_f32_32x32x2_f32 v[108:123], v185, v30, v[108:123]
	v_mfma_f32_32x32x2_f32 v[124:139], v185, v31, v[124:139]
	v_mfma_f32_32x32x2_f32 v[146:161], v185, v2, v[146:161]
	v_mfma_f32_32x32x2_f32 v[162:177], v185, v3, v[162:177]
	s_setprio 0
	s_nop 7
	s_nop 7
	s_nop 7
	v_permlane32_swap_b32_e32 v108, v146
	v_permlane32_swap_b32_e32 v124, v162
	v_permlane32_swap_b32_e32 v109, v147
	v_permlane32_swap_b32_e32 v125, v163
	v_permlane32_swap_b32_e32 v110, v148
	v_permlane32_swap_b32_e32 v126, v164
	v_permlane32_swap_b32_e32 v111, v149
	v_permlane32_swap_b32_e32 v127, v165
	v_permlane32_swap_b32_e32 v112, v150
	v_permlane32_swap_b32_e32 v128, v166
	v_permlane32_swap_b32_e32 v113, v151
	v_permlane32_swap_b32_e32 v129, v167
	v_permlane32_swap_b32_e32 v114, v152
	v_permlane32_swap_b32_e32 v130, v168
	v_permlane32_swap_b32_e32 v115, v153
	v_permlane32_swap_b32_e32 v131, v169
	v_permlane32_swap_b32_e32 v116, v154
	v_permlane32_swap_b32_e32 v132, v170
	v_permlane32_swap_b32_e32 v117, v155
	v_permlane32_swap_b32_e32 v133, v171
	v_permlane32_swap_b32_e32 v118, v156
	v_permlane32_swap_b32_e32 v134, v172
	v_permlane32_swap_b32_e32 v119, v157
	v_permlane32_swap_b32_e32 v135, v173
	v_permlane32_swap_b32_e32 v120, v158
	v_permlane32_swap_b32_e32 v136, v174
	v_permlane32_swap_b32_e32 v121, v159
	v_permlane32_swap_b32_e32 v137, v175
	v_permlane32_swap_b32_e32 v122, v160
	v_permlane32_swap_b32_e32 v138, v176
	v_permlane32_swap_b32_e32 v123, v161
	v_permlane32_swap_b32_e32 v139, v177
	v_mul_f32_e32 v188, v34, v37
	v_mul_f32_e32 v189, v35, v37
	v_fma_f32 v190, v32, v36, -v188
	v_fma_f32 v191, v33, v36, v189
	v_add_f32_e32 v36, v190, v108
	v_add_f32_e32 v37, v191, v124
	v_mul_f32_e32 v188, v34, v37
	v_mul_f32_e32 v189, v35, v37
	v_fma_f32 v190, v32, v36, -v188
	v_fma_f32 v191, v33, v36, v189
	v_add_f32_e32 v36, v190, v109
	v_add_f32_e32 v37, v191, v125
	v_mul_f32_e32 v188, v34, v37
	v_mul_f32_e32 v189, v35, v37
	v_fma_f32 v190, v32, v36, -v188
	v_fma_f32 v191, v33, v36, v189
	v_add_f32_e32 v36, v190, v110
	v_add_f32_e32 v37, v191, v126
	v_mul_f32_e32 v188, v34, v37
	v_mul_f32_e32 v189, v35, v37
	v_fma_f32 v190, v32, v36, -v188
	v_fma_f32 v191, v33, v36, v189
	v_add_f32_e32 v36, v190, v111
	v_add_f32_e32 v37, v191, v127
	v_mul_f32_e32 v188, v34, v37
	v_mul_f32_e32 v189, v35, v37
; __device__ __forceinline__ void s5_pass1(const Params& p, int layer, int task, char* sm) {
;     ...
;   for (int l = 0; l < 128; l++) S5_STEP(sU + l * 16)
;   *(float2*)(p.END + (((size_t)(b * 128 + c) * 32 + g) * 64 + lane) * 2) = make_float2(sr, si);
	v_fma_f32 v190, v32, v36, -v188
	v_fma_f32 v191, v33, v36, v189
	v_add_f32_e32 v36, v190, v146
	v_add_f32_e32 v37, v191, v162
	v_mul_f32_e32 v188, v34, v37
	v_mul_f32_e32 v189, v35, v37
	v_fma_f32 v190, v32, v36, -v188
	v_fma_f32 v191, v33, v36, v189
	v_add_f32_e32 v36, v190, v147
	v_add_f32_e32 v37, v191, v163
	v_mul_f32_e32 v188, v34, v37
	v_mul_f32_e32 v189, v35, v37
	v_fma_f32 v190, v32, v36, -v188
	v_fma_f32 v191, v33, v36, v189
	v_add_f32_e32 v36, v190, v148
	v_add_f32_e32 v37, v191, v164
	v_mul_f32_e32 v188, v34, v37
	v_mul_f32_e32 v189, v35, v37
	v_fma_f32 v190, v32, v36, -v188
	v_fma_f32 v191, v33, v36, v189
	v_add_f32_e32 v36, v190, v149
	v_add_f32_e32 v37, v191, v165
	v_mul_f32_e32 v188, v34, v37
	v_mul_f32_e32 v189, v35, v37
	v_fma_f32 v190, v32, v36, -v188
	v_fma_f32 v191, v33, v36, v189
	v_add_f32_e32 v36, v190, v112
	v_add_f32_e32 v37, v191, v128
	v_mul_f32_e32 v188, v34, v37
	v_mul_f32_e32 v189, v35, v37
	v_fma_f32 v190, v32, v36, -v188
	v_fma_f32 v191, v33, v36, v189
	v_add_f32_e32 v36, v190, v113
	v_add_f32_e32 v37, v191, v129
	v_mul_f32_e32 v188, v34, v37
	v_mul_f32_e32 v189, v35, v37
	v_fma_f32 v190, v32, v36, -v188
	v_fma_f32 v191, v33, v36, v189
	v_add_f32_e32 v36, v190, v114
	v_add_f32_e32 v37, v191, v130
	v_mul_f32_e32 v188, v34, v37
	v_mul_f32_e32 v189, v35, v37
	v_fma_f32 v190, v32, v36, -v188
	v_fma_f32 v191, v33, v36, v189
	v_add_f32_e32 v36, v190, v115
	v_add_f32_e32 v37, v191, v131
	v_mul_f32_e32 v188, v34, v37
	v_mul_f32_e32 v189, v35, v37
	v_fma_f32 v190, v32, v36, -v188
	v_fma_f32 v191, v33, v36, v189
	v_add_f32_e32 v36, v190, v150
	v_add_f32_e32 v37, v191, v166
	v_mul_f32_e32 v188, v34, v37
	v_mul_f32_e32 v189, v35, v37
	v_fma_f32 v190, v32, v36, -v188
	v_fma_f32 v191, v33, v36, v189
	v_add_f32_e32 v36, v190, v151
	v_add_f32_e32 v37, v191, v167
	v_mul_f32_e32 v188, v34, v37
	v_mul_f32_e32 v189, v35, v37
	v_fma_f32 v190, v32, v36, -v188
	v_fma_f32 v191, v33, v36, v189
	v_add_f32_e32 v36, v190, v152
	v_add_f32_e32 v37, v191, v168
	v_mul_f32_e32 v188, v34, v37
	v_mul_f32_e32 v189, v35, v37
	v_fma_f32 v190, v32, v36, -v188
	v_fma_f32 v191, v33, v36, v189
	v_add_f32_e32 v36, v190, v153
	v_add_f32_e32 v37, v191, v169
	v_mul_f32_e32 v188, v34, v37
	v_mul_f32_e32 v189, v35, v37
	v_fma_f32 v190, v32, v36, -v188
	v_fma_f32 v191, v33, v36, v189
	v_add_f32_e32 v36, v190, v116
	v_add_f32_e32 v37, v191, v132
	v_mul_f32_e32 v188, v34, v37
	v_mul_f32_e32 v189, v35, v37
	v_fma_f32 v190, v32, v36, -v188
	v_fma_f32 v191, v33, v36, v189
	v_add_f32_e32 v36, v190, v117
	v_add_f32_e32 v37, v191, v133
	v_mul_f32_e32 v188, v34, v37
	v_mul_f32_e32 v189, v35, v37
	v_fma_f32 v190, v32, v36, -v188
	v_fma_f32 v191, v33, v36, v189
	v_add_f32_e32 v36, v190, v118
	v_add_f32_e32 v37, v191, v134
	v_mul_f32_e32 v188, v34, v37
	v_mul_f32_e32 v189, v35, v37
	v_fma_f32 v190, v32, v36, -v188
	v_fma_f32 v191, v33, v36, v189
	v_add_f32_e32 v36, v190, v119
	v_add_f32_e32 v37, v191, v135
	v_mul_f32_e32 v188, v34, v37
	v_mul_f32_e32 v189, v35, v37
	v_fma_f32 v190, v32, v36, -v188
	v_fma_f32 v191, v33, v36, v189
	v_add_f32_e32 v36, v190, v154
	v_add_f32_e32 v37, v191, v170
	v_mul_f32_e32 v188, v34, v37
	v_mul_f32_e32 v189, v35, v37
	v_fma_f32 v190, v32, v36, -v188
	v_fma_f32 v191, v33, v36, v189
	v_add_f32_e32 v36, v190, v155
	v_add_f32_e32 v37, v191, v171
	v_mul_f32_e32 v188, v34, v37
	v_mul_f32_e32 v189, v35, v37
	v_fma_f32 v190, v32, v36, -v188
	v_fma_f32 v191, v33, v36, v189
	v_add_f32_e32 v36, v190, v156
	v_add_f32_e32 v37, v191, v172
	v_mul_f32_e32 v188, v34, v37
	v_mul_f32_e32 v189, v35, v37
	v_fma_f32 v190, v32, v36, -v188
	v_fma_f32 v191, v33, v36, v189
	v_add_f32_e32 v36, v190, v157
	v_add_f32_e32 v37, v191, v173
	v_mul_f32_e32 v188, v34, v37
	v_mul_f32_e32 v189, v35, v37
	v_fma_f32 v190, v32, v36, -v188
	v_fma_f32 v191, v33, v36, v189
	v_add_f32_e32 v36, v190, v120
	v_add_f32_e32 v37, v191, v136
	v_mul_f32_e32 v188, v34, v37
	v_mul_f32_e32 v189, v35, v37
	v_fma_f32 v190, v32, v36, -v188
	v_fma_f32 v191, v33, v36, v189
	v_add_f32_e32 v36, v190, v121
	v_add_f32_e32 v37, v191, v137
	v_mul_f32_e32 v188, v34, v37
	v_mul_f32_e32 v189, v35, v37
	v_fma_f32 v190, v32, v36, -v188
	v_fma_f32 v191, v33, v36, v189
	v_add_f32_e32 v36, v190, v122
	v_add_f32_e32 v37, v191, v138
	v_mul_f32_e32 v188, v34, v37
	v_mul_f32_e32 v189, v35, v37
	v_fma_f32 v190, v32, v36, -v188
	v_fma_f32 v191, v33, v36, v189
	v_add_f32_e32 v36, v190, v123
	v_add_f32_e32 v37, v191, v139
	v_mul_f32_e32 v188, v34, v37
	v_mul_f32_e32 v189, v35, v37
	v_fma_f32 v190, v32, v36, -v188
	v_fma_f32 v191, v33, v36, v189
	v_add_f32_e32 v36, v190, v158
	v_add_f32_e32 v37, v191, v174
	v_mul_f32_e32 v188, v34, v37
	v_mul_f32_e32 v189, v35, v37
	v_fma_f32 v190, v32, v36, -v188
	v_fma_f32 v191, v33, v36, v189
	v_add_f32_e32 v36, v190, v159
	v_add_f32_e32 v37, v191, v175
	v_mul_f32_e32 v188, v34, v37
	v_mul_f32_e32 v189, v35, v37
	v_fma_f32 v190, v32, v36, -v188
	v_fma_f32 v191, v33, v36, v189
	v_add_f32_e32 v36, v190, v160
	v_add_f32_e32 v37, v191, v176
	v_mul_f32_e32 v188, v34, v37
	v_mul_f32_e32 v189, v35, v37
	v_fma_f32 v190, v32, v36, -v188
	v_fma_f32 v191, v33, v36, v189
	v_add_f32_e32 v36, v190, v161
	v_add_f32_e32 v37, v191, v177
	v_mov_b32_e32 v38, v37
	s_lshl_b32 s1, s1, 12
	s_lshl_b32 s0, s0, 5
	s_or_b32 s0, s0, s1
	v_or_b32_e32 v0, s0, v40
	v_lshlrev_b32_e32 v1, 1, v39
	v_readlane_b32 s0, v253, 38
	v_lshl_or_b32 v144, v0, 7, v1
	v_readlane_b32 s1, v253, 39
	v_readlane_b32 s2, v253, 40
	v_readlane_b32 s3, v253, 41
	v_lshl_add_u64 v[0:1], v[144:145], 2, s[0:1]
	v_readlane_b32 s4, v253, 42
	v_readlane_b32 s5, v253, 43
	v_readlane_b32 s6, v253, 44
	v_readlane_b32 s7, v253, 45
	global_store_dwordx2 v[0:1], v[36:37], off

; __device__ __forceinline__ bf f2bf(float f) { return (bf)(pk2(f, 0.f) & 0xFFFFu); }
; __device__ __forceinline__ void s5_pass2(const Params& p, int layer, int task, char* sm) {
;     ...
;     for (int sub = 0; sub < 4; sub++) {
;       __builtin_amdgcn_wave_barrier();
;       if (lane < 32) s5_st_u(sU + lane * 16, ua, ub);
;       {
;         const int nsub = (sub + 1) & 3; const int ng = g + (sub == 3 ? 1 : 0);
;         if (sub < 3 || gi < 7) s5_ld_u(p, tok0 + nsub * 32 + (lane & 31), ng, ua, ub);
;       }
;       __builtin_amdgcn_wave_barrier();
;       for (int l = 0; l < 32; l++) {
;         S5_STEP(sU + l * 16)
;         sS[l * 136 + lane] = f2bf(sr); sS[l * 136 + 64 + lane] = f2bf(si);
;       }
.LBB0_1796:
	v_add_u32_e32 v103, v79, v40
	v_and_b32_e32 v43, 31, v202
	v_lshrrev_b32_e32 v42, 5, v202
	v_lshlrev_b32_e32 v43, 6, v43
	v_lshl_add_u32 v43, v42, 2, v43
	v_add_u32_e32 v43, v79, v43
	ds_read2_b32 v[170:171], v43 offset0:0 offset1:2
	ds_read2_b32 v[172:173], v43 offset0:4 offset1:6
	ds_read2_b32 v[174:175], v43 offset0:8 offset1:10
	ds_read2_b32 v[176:177], v43 offset0:12 offset1:14
	s_waitcnt lgkmcnt(0)
	s_setprio 1
	v_mfma_f32_32x32x2_f32 v[104:119], v170, v52, 0
	v_mfma_f32_32x32x2_f32 v[120:135], v170, v53, 0
	v_mfma_f32_32x32x2_f32 v[152:167], v170, v20, 0
	v_mfma_f32_32x32x2_f32 v[136:151], v170, v21, 0
	v_mfma_f32_32x32x2_f32 v[104:119], v171, v54, v[104:119]
	v_mfma_f32_32x32x2_f32 v[120:135], v171, v55, v[120:135]
	v_mfma_f32_32x32x2_f32 v[152:167], v171, v22, v[152:167]
	v_mfma_f32_32x32x2_f32 v[136:151], v171, v23, v[136:151]
	v_mfma_f32_32x32x2_f32 v[104:119], v172, v56, v[104:119]
	v_mfma_f32_32x32x2_f32 v[120:135], v172, v57, v[120:135]
	v_mfma_f32_32x32x2_f32 v[152:167], v172, v16, v[152:167]
	v_mfma_f32_32x32x2_f32 v[136:151], v172, v17, v[136:151]
	v_mfma_f32_32x32x2_f32 v[104:119], v173, v58, v[104:119]
	v_mfma_f32_32x32x2_f32 v[120:135], v173, v59, v[120:135]
	v_mfma_f32_32x32x2_f32 v[152:167], v173, v18, v[152:167]
	v_mfma_f32_32x32x2_f32 v[136:151], v173, v19, v[136:151]
	v_mfma_f32_32x32x2_f32 v[104:119], v174, v60, v[104:119]
	v_mfma_f32_32x32x2_f32 v[120:135], v174, v61, v[120:135]
	v_mfma_f32_32x32x2_f32 v[152:167], v174, v12, v[152:167]
	v_mfma_f32_32x32x2_f32 v[136:151], v174, v13, v[136:151]
	v_mfma_f32_32x32x2_f32 v[104:119], v175, v62, v[104:119]
	v_mfma_f32_32x32x2_f32 v[120:135], v175, v63, v[120:135]
	v_mfma_f32_32x32x2_f32 v[152:167], v175, v14, v[152:167]
	v_mfma_f32_32x32x2_f32 v[136:151], v175, v15, v[136:151]
	v_mfma_f32_32x32x2_f32 v[104:119], v176, v64, v[104:119]
	v_mfma_f32_32x32x2_f32 v[120:135], v176, v65, v[120:135]
	v_mfma_f32_32x32x2_f32 v[152:167], v176, v8, v[152:167]
	v_mfma_f32_32x32x2_f32 v[136:151], v176, v9, v[136:151]
	v_mfma_f32_32x32x2_f32 v[104:119], v177, v66, v[104:119]
	v_mfma_f32_32x32x2_f32 v[120:135], v177, v67, v[120:135]
	v_mfma_f32_32x32x2_f32 v[152:167], v177, v10, v[152:167]
	v_mfma_f32_32x32x2_f32 v[136:151], v177, v11, v[136:151]
	s_setprio 0
	s_nop 7
	s_nop 7
	s_nop 7
	v_permlane32_swap_b32_e32 v104, v152
	v_permlane32_swap_b32_e32 v120, v136
	v_permlane32_swap_b32_e32 v105, v153
	v_permlane32_swap_b32_e32 v121, v137
	v_permlane32_swap_b32_e32 v106, v154
	v_permlane32_swap_b32_e32 v122, v138
	v_permlane32_swap_b32_e32 v107, v155
	v_permlane32_swap_b32_e32 v123, v139
	v_permlane32_swap_b32_e32 v108, v156
	v_permlane32_swap_b32_e32 v124, v140
	v_permlane32_swap_b32_e32 v109, v157
	v_permlane32_swap_b32_e32 v125, v141
	v_permlane32_swap_b32_e32 v110, v158
	v_permlane32_swap_b32_e32 v126, v142
	v_permlane32_swap_b32_e32 v111, v159
	v_permlane32_swap_b32_e32 v127, v143
	v_permlane32_swap_b32_e32 v112, v160
	v_permlane32_swap_b32_e32 v128, v144
	v_permlane32_swap_b32_e32 v113, v161
	v_permlane32_swap_b32_e32 v129, v145
	v_permlane32_swap_b32_e32 v114, v162
	v_permlane32_swap_b32_e32 v130, v146
	v_permlane32_swap_b32_e32 v115, v163
	v_permlane32_swap_b32_e32 v131, v147
	v_permlane32_swap_b32_e32 v116, v164
	v_permlane32_swap_b32_e32 v132, v148
	v_permlane32_swap_b32_e32 v117, v165
	v_permlane32_swap_b32_e32 v133, v149
	v_permlane32_swap_b32_e32 v118, v166
	v_permlane32_swap_b32_e32 v134, v150
	v_permlane32_swap_b32_e32 v119, v167
	v_permlane32_swap_b32_e32 v135, v151
	s_waitcnt vmcnt(5)
	v_mul_f32_e32 v76, v74, v71
	v_mul_f32_e32 v77, v75, v71
	v_fma_f32 v40, v68, v70, -v76
	v_fma_f32 v41, v69, v70, v77
	v_add_f32_e32 v70, v40, v104
	v_add_f32_e32 v71, v41, v120
	v_mul_f32_e32 v76, v74, v71
	v_mul_f32_e32 v77, v75, v71
	v_cvt_pk_bf16_f32 v42, v70, v71
	v_fma_f32 v40, v68, v70, -v76
	v_fma_f32 v41, v69, v70, v77
	ds_write_b16 v103, v42
	v_add_f32_e32 v70, v40, v105
	v_add_f32_e32 v71, v41, v121
	ds_write_b16_d16_hi v103, v42 offset:128
	v_mul_f32_e32 v76, v74, v71
	v_mul_f32_e32 v77, v75, v71
	v_cvt_pk_bf16_f32 v42, v70, v71
	v_fma_f32 v40, v68, v70, -v76
	v_fma_f32 v41, v69, v70, v77
	ds_write_b16 v103, v42 offset:272
	v_add_f32_e32 v70, v40, v106
	v_add_f32_e32 v71, v41, v122
	ds_write_b16_d16_hi v103, v42 offset:400
	v_mul_f32_e32 v76, v74, v71
	v_mul_f32_e32 v77, v75, v71
	v_cvt_pk_bf16_f32 v42, v70, v71
	v_fma_f32 v40, v68, v70, -v76
	v_fma_f32 v41, v69, v70, v77
	ds_write_b16 v103, v42 offset:544
	v_add_f32_e32 v70, v40, v107
	v_add_f32_e32 v71, v41, v123
	ds_write_b16_d16_hi v103, v42 offset:672
	v_mul_f32_e32 v76, v74, v71
	v_mul_f32_e32 v77, v75, v71
	v_cvt_pk_bf16_f32 v42, v70, v71
	v_fma_f32 v40, v68, v70, -v76
	v_fma_f32 v41, v69, v70, v77
	ds_write_b16 v103, v42 offset:816
	v_add_f32_e32 v70, v40, v152
	v_add_f32_e32 v71, v41, v136
	ds_write_b16_d16_hi v103, v42 offset:944
	v_mul_f32_e32 v76, v74, v71
	v_mul_f32_e32 v77, v75, v71
	v_cvt_pk_bf16_f32 v42, v70, v71
	v_fma_f32 v40, v68, v70, -v76
	v_fma_f32 v41, v69, v70, v77
	ds_write_b16 v103, v42 offset:1088
	v_add_f32_e32 v70, v40, v153
	v_add_f32_e32 v71, v41, v137
	ds_write_b16_d16_hi v103, v42 offset:1216
	v_mul_f32_e32 v76, v74, v71
	v_mul_f32_e32 v77, v75, v71
	v_cvt_pk_bf16_f32 v42, v70, v71
	v_fma_f32 v40, v68, v70, -v76
	v_fma_f32 v41, v69, v70, v77
	ds_write_b16 v103, v42 offset:1360
	v_add_f32_e32 v70, v40, v154
	v_add_f32_e32 v71, v41, v138
	ds_write_b16_d16_hi v103, v42 offset:1488
	v_mul_f32_e32 v76, v74, v71
	v_mul_f32_e32 v77, v75, v71
	v_cvt_pk_bf16_f32 v42, v70, v71
	v_fma_f32 v40, v68, v70, -v76
	v_fma_f32 v41, v69, v70, v77
	ds_write_b16 v103, v42 offset:1632
	v_add_f32_e32 v70, v40, v155
; __device__ __forceinline__ bf f2bf(float f) { return (bf)(pk2(f, 0.f) & 0xFFFFu); }
; __device__ __forceinline__ void s5_pass2(const Params& p, int layer, int task, char* sm) {
;     ...
;       for (int l = 0; l < 32; l++) {
;         S5_STEP(sU + l * 16)
;         sS[l * 136 + lane] = f2bf(sr); sS[l * 136 + 64 + lane] = f2bf(si);
;       }
	v_add_f32_e32 v71, v41, v139
	ds_write_b16_d16_hi v103, v42 offset:1760
	v_mul_f32_e32 v76, v74, v71
	v_mul_f32_e32 v77, v75, v71
	v_cvt_pk_bf16_f32 v42, v70, v71
	v_fma_f32 v40, v68, v70, -v76
	v_fma_f32 v41, v69, v70, v77
	ds_write_b16 v103, v42 offset:1904
	v_add_f32_e32 v70, v40, v108
	v_add_f32_e32 v71, v41, v124
	ds_write_b16_d16_hi v103, v42 offset:2032
	v_mul_f32_e32 v76, v74, v71
	v_mul_f32_e32 v77, v75, v71
	v_cvt_pk_bf16_f32 v42, v70, v71
	v_fma_f32 v40, v68, v70, -v76
	v_fma_f32 v41, v69, v70, v77
	ds_write_b16 v103, v42 offset:2176
	v_add_f32_e32 v70, v40, v109
	v_add_f32_e32 v71, v41, v125
	ds_write_b16_d16_hi v103, v42 offset:2304
	v_mul_f32_e32 v76, v74, v71
	v_mul_f32_e32 v77, v75, v71
	v_cvt_pk_bf16_f32 v42, v70, v71
	v_fma_f32 v40, v68, v70, -v76
	v_fma_f32 v41, v69, v70, v77
	ds_write_b16 v103, v42 offset:2448
	v_add_f32_e32 v70, v40, v110
	v_add_f32_e32 v71, v41, v126
	ds_write_b16_d16_hi v103, v42 offset:2576
	v_mul_f32_e32 v76, v74, v71
	v_mul_f32_e32 v77, v75, v71
	v_cvt_pk_bf16_f32 v42, v70, v71
	v_fma_f32 v40, v68, v70, -v76
	v_fma_f32 v41, v69, v70, v77
	ds_write_b16 v103, v42 offset:2720
	v_add_f32_e32 v70, v40, v111
	v_add_f32_e32 v71, v41, v127
	ds_write_b16_d16_hi v103, v42 offset:2848
	v_mul_f32_e32 v76, v74, v71
	v_mul_f32_e32 v77, v75, v71
	v_cvt_pk_bf16_f32 v42, v70, v71
	v_fma_f32 v40, v68, v70, -v76
	v_fma_f32 v41, v69, v70, v77
	ds_write_b16 v103, v42 offset:2992
	v_add_f32_e32 v70, v40, v156
	v_add_f32_e32 v71, v41, v140
	ds_write_b16_d16_hi v103, v42 offset:3120
	v_mul_f32_e32 v76, v74, v71
	v_mul_f32_e32 v77, v75, v71
	v_cvt_pk_bf16_f32 v42, v70, v71
	v_fma_f32 v40, v68, v70, -v76
	v_fma_f32 v41, v69, v70, v77
	ds_write_b16 v103, v42 offset:3264
	v_add_f32_e32 v70, v40, v157
	v_add_f32_e32 v71, v41, v141
	ds_write_b16_d16_hi v103, v42 offset:3392
	v_mul_f32_e32 v76, v74, v71
	v_mul_f32_e32 v77, v75, v71
	v_cvt_pk_bf16_f32 v42, v70, v71
	v_fma_f32 v40, v68, v70, -v76
	v_fma_f32 v41, v69, v70, v77
	ds_write_b16 v103, v42 offset:3536
	v_add_f32_e32 v70, v40, v158
	v_add_f32_e32 v71, v41, v142
	ds_write_b16_d16_hi v103, v42 offset:3664
	v_mul_f32_e32 v76, v74, v71
	v_mul_f32_e32 v77, v75, v71
	v_cvt_pk_bf16_f32 v42, v70, v71
	v_fma_f32 v40, v68, v70, -v76
	v_fma_f32 v41, v69, v70, v77
	ds_write_b16 v103, v42 offset:3808
	v_add_f32_e32 v70, v40, v159
	v_add_f32_e32 v71, v41, v143
	ds_write_b16_d16_hi v103, v42 offset:3936
	v_mul_f32_e32 v76, v74, v71
	v_mul_f32_e32 v77, v75, v71
	v_cvt_pk_bf16_f32 v42, v70, v71
	v_fma_f32 v40, v68, v70, -v76
	v_fma_f32 v41, v69, v70, v77
	ds_write_b16 v103, v42 offset:4080
	v_add_f32_e32 v70, v40, v112
	v_add_f32_e32 v71, v41, v128
	ds_write_b16_d16_hi v103, v42 offset:4208
	v_mul_f32_e32 v76, v74, v71
	v_mul_f32_e32 v77, v75, v71
	v_cvt_pk_bf16_f32 v42, v70, v71
	v_fma_f32 v40, v68, v70, -v76
	v_fma_f32 v41, v69, v70, v77
	ds_write_b16 v103, v42 offset:4352
	v_add_f32_e32 v70, v40, v113
	v_add_f32_e32 v71, v41, v129
	ds_write_b16_d16_hi v103, v42 offset:4480
	v_mul_f32_e32 v76, v74, v71
	v_mul_f32_e32 v77, v75, v71
	v_cvt_pk_bf16_f32 v42, v70, v71
	v_fma_f32 v40, v68, v70, -v76
	v_fma_f32 v41, v69, v70, v77
	ds_write_b16 v103, v42 offset:4624
	v_add_f32_e32 v70, v40, v114
	v_add_f32_e32 v71, v41, v130
	ds_write_b16_d16_hi v103, v42 offset:4752
	v_mul_f32_e32 v76, v74, v71
	v_mul_f32_e32 v77, v75, v71
	v_cvt_pk_bf16_f32 v42, v70, v71
	v_fma_f32 v40, v68, v70, -v76
	v_fma_f32 v41, v69, v70, v77
	ds_write_b16 v103, v42 offset:4896
	v_add_f32_e32 v70, v40, v115
	v_add_f32_e32 v71, v41, v131
	ds_write_b16_d16_hi v103, v42 offset:5024
	v_mul_f32_e32 v76, v74, v71
	v_mul_f32_e32 v77, v75, v71
	v_cvt_pk_bf16_f32 v42, v70, v71
	v_fma_f32 v40, v68, v70, -v76
	v_fma_f32 v41, v69, v70, v77
	ds_write_b16 v103, v42 offset:5168
	v_add_f32_e32 v70, v40, v160
	v_add_f32_e32 v71, v41, v144
	ds_write_b16_d16_hi v103, v42 offset:5296
	v_mul_f32_e32 v76, v74, v71
	v_mul_f32_e32 v77, v75, v71
	v_cvt_pk_bf16_f32 v42, v70, v71
	v_fma_f32 v40, v68, v70, -v76
	v_fma_f32 v41, v69, v70, v77
	ds_write_b16 v103, v42 offset:5440
	v_add_f32_e32 v70, v40, v161
	v_add_f32_e32 v71, v41, v145
	ds_write_b16_d16_hi v103, v42 offset:5568
	v_mul_f32_e32 v76, v74, v71
	v_mul_f32_e32 v77, v75, v71
	v_cvt_pk_bf16_f32 v42, v70, v71
	v_fma_f32 v40, v68, v70, -v76
	v_fma_f32 v41, v69, v70, v77
	ds_write_b16 v103, v42 offset:5712
	v_add_f32_e32 v70, v40, v162
	v_add_f32_e32 v71, v41, v146
	ds_write_b16_d16_hi v103, v42 offset:5840
	v_mul_f32_e32 v76, v74, v71
	v_mul_f32_e32 v77, v75, v71
	v_cvt_pk_bf16_f32 v42, v70, v71
	v_fma_f32 v40, v68, v70, -v76
	v_fma_f32 v41, v69, v70, v77
	ds_write_b16 v103, v42 offset:5984
	v_add_f32_e32 v70, v40, v163
	v_add_f32_e32 v71, v41, v147
	ds_write_b16_d16_hi v103, v42 offset:6112
	v_mul_f32_e32 v76, v74, v71
	v_mul_f32_e32 v77, v75, v71
	v_cvt_pk_bf16_f32 v42, v70, v71
	v_fma_f32 v40, v68, v70, -v76
	v_fma_f32 v41, v69, v70, v77
	ds_write_b16 v103, v42 offset:6256
	v_add_f32_e32 v70, v40, v116
	v_add_f32_e32 v71, v41, v132
	ds_write_b16_d16_hi v103, v42 offset:6384
	v_mul_f32_e32 v76, v74, v71
	v_mul_f32_e32 v77, v75, v71
	v_cvt_pk_bf16_f32 v42, v70, v71
	v_fma_f32 v40, v68, v70, -v76
	v_fma_f32 v41, v69, v70, v77
	ds_write_b16 v103, v42 offset:6528
	v_add_f32_e32 v70, v40, v117
	v_add_f32_e32 v71, v41, v133
	ds_write_b16_d16_hi v103, v42 offset:6656
	v_mul_f32_e32 v76, v74, v71
	v_mul_f32_e32 v77, v75, v71
	v_cvt_pk_bf16_f32 v42, v70, v71
	v_fma_f32 v40, v68, v70, -v76
	v_fma_f32 v41, v69, v70, v77
	ds_write_b16 v103, v42 offset:6800
	v_add_f32_e32 v70, v40, v118
	v_add_f32_e32 v71, v41, v134
	ds_write_b16_d16_hi v103, v42 offset:6928
	v_mul_f32_e32 v76, v74, v71
; __device__ __forceinline__ float ozero() { float z = 0.f; asm volatile("" : "+v"(z)); return z; }
; __device__ __forceinline__ bf f2bf(float f) { return (bf)(pk2(f, 0.f) & 0xFFFFu); }
; __device__ __forceinline__ f32x4 mfma16(bf16x8 a, bf16x8 b, f32x4 c) { return __builtin_amdgcn_mfma_f32_16x16x32_bf16(a, b, c, 0, 0, 0); }
; __device__ __forceinline__ void s5_pass2(const Params& p, int layer, int task, char* sm) {
;     ...
;       for (int l = 0; l < 32; l++) {
;         S5_STEP(sU + l * 16)
;         sS[l * 136 + lane] = f2bf(sr); sS[l * 136 + 64 + lane] = f2bf(si);
;       }
;       __builtin_amdgcn_wave_barrier();
; #pragma unroll
;       for (int mb = 0; mb < 2; mb++) {
;         const float z_ = ozero(); f32x4 acc = {z_, z_, z_, z_};
; #pragma unroll
;         for (int ks = 0; ks < 4; ks++) {
;           bf16x8 af = *(const bf16x8*)(sS + (16 * mb + (lane & 15)) * 136 + ks * 32 + 8 * (lane >> 4));
;           acc = mfma16(af, cf[ks], acc);
;         }
; #pragma unroll
;         for (int r = 0; r < 4; r++) {
;           const int l = 16 * mb + 4 * (lane >> 4) + r;
;           float y = acc[r] + dsk * sU[l * 16 + (lane & 15)];
;           p.YG[(tok0 + sub * 32 + l) * 512 + g * 16 + (lane & 15)] = f2bf(geluf_(y));
;         }
;       }
	v_mul_f32_e32 v77, v75, v71
	v_cvt_pk_bf16_f32 v42, v70, v71
	v_fma_f32 v40, v68, v70, -v76
	v_fma_f32 v41, v69, v70, v77
	ds_write_b16 v103, v42 offset:7072
	v_add_f32_e32 v70, v40, v119
	v_add_f32_e32 v71, v41, v135
	ds_write_b16_d16_hi v103, v42 offset:7200
	v_mul_f32_e32 v76, v74, v71
	v_mul_f32_e32 v77, v75, v71
	v_cvt_pk_bf16_f32 v42, v70, v71
	v_fma_f32 v40, v68, v70, -v76
	v_fma_f32 v41, v69, v70, v77
	ds_write_b16 v103, v42 offset:7344
	v_add_f32_e32 v70, v40, v164
	v_add_f32_e32 v71, v41, v148
	ds_write_b16_d16_hi v103, v42 offset:7472
	v_mul_f32_e32 v76, v74, v71
	v_mul_f32_e32 v77, v75, v71
	v_cvt_pk_bf16_f32 v42, v70, v71
	v_fma_f32 v40, v68, v70, -v76
	v_fma_f32 v41, v69, v70, v77
	ds_write_b16 v103, v42 offset:7616
	v_add_f32_e32 v70, v40, v165
	v_add_f32_e32 v71, v41, v149
	ds_write_b16_d16_hi v103, v42 offset:7744
	v_mul_f32_e32 v76, v74, v71
	v_mul_f32_e32 v77, v75, v71
	v_cvt_pk_bf16_f32 v42, v70, v71
	v_fma_f32 v40, v68, v70, -v76
	v_fma_f32 v41, v69, v70, v77
	ds_write_b16 v103, v42 offset:7888
	v_add_f32_e32 v70, v40, v166
	v_add_f32_e32 v71, v41, v150
	ds_write_b16_d16_hi v103, v42 offset:8016
	v_mul_f32_e32 v76, v74, v71
	v_mul_f32_e32 v77, v75, v71
	v_cvt_pk_bf16_f32 v42, v70, v71
	v_fma_f32 v40, v68, v70, -v76
	v_fma_f32 v41, v69, v70, v77
	ds_write_b16 v103, v42 offset:8160
	v_add_f32_e32 v70, v40, v167
	v_add_f32_e32 v71, v41, v151
	ds_write_b16_d16_hi v103, v42 offset:8288
	v_cvt_pk_bf16_f32 v42, v70, v71
	ds_write_b16 v103, v42 offset:8432
	ds_write_b16_d16_hi v103, v42 offset:8560
	s_waitcnt lgkmcnt(0)
	v_mov_b32_e32 v145, 0
	v_mov_b32_e32 v40, v145
	ds_read_b128 v[104:107], v100 offset:2048
	ds_read_b32 v76, v83
	v_mov_b32_e32 v41, v40
	v_mov_b32_e32 v42, v40
	v_mov_b32_e32 v43, v40
	s_lshl_b32 s9, s11, 5
	v_mov_b32_e32 v77, s5
	s_cmp_eq_u32 s8, 4
	s_waitcnt vmcnt(4) lgkmcnt(1)
	v_mfma_f32_16x16x32_bf16 v[40:43], v[104:107], v[24:27], v[40:43]
	ds_read_b128 v[104:107], v100 offset:2112
	s_waitcnt vmcnt(3) lgkmcnt(0)
	v_mfma_f32_16x16x32_bf16 v[40:43], v[104:107], v[28:31], v[40:43]
	ds_read_b128 v[104:107], v100 offset:2176
	s_waitcnt vmcnt(2) lgkmcnt(0)
	v_mfma_f32_16x16x32_bf16 v[40:43], v[104:107], v[32:35], v[40:43]
	ds_read_b128 v[104:107], v100 offset:2240
	s_waitcnt vmcnt(1) lgkmcnt(0)
	v_mfma_f32_16x16x32_bf16 v[40:43], v[104:107], v[36:39], v[40:43]
	s_waitcnt vmcnt(0)
	s_nop 6
	v_fma_f32 v40, v102, v76, v40
	v_mul_f32_e32 v76, 0x3d372713, v40
	v_mul_f32_e32 v76, v40, v76
	v_fma_f32 v76, v40, v76, v40
	v_mul_f32_e32 v76, 0x3f4c422a, v76
	v_add_f32_e32 v76, v76, v76
	v_mul_f32_e32 v76, 0x3fb8aa3b, v76
	v_exp_f32_e32 v76, v76
	v_mul_f32_e32 v40, 0.5, v40
	v_add_f32_e32 v76, 1.0, v76
	v_rcp_f32_e32 v76, v76
	s_nop 0
	v_fma_f32 v76, v76, -2.0, 1.0
	v_add_f32_e32 v76, 1.0, v76
	v_mul_f32_e32 v40, v40, v76
	v_or_b32_e32 v76, s9, v82
	v_or_b32_e32 v76, s4, v76
	v_lshlrev_b64 v[104:105], 10, v[76:77]
	v_cvt_pk_bf16_f32 v40, v40, s0
	v_lshl_add_u64 v[104:105], v[72:73], 0, v[104:105]
	global_store_short v[104:105], v40, off
	ds_read_b32 v40, v85
	s_waitcnt lgkmcnt(0)
	v_fma_f32 v40, v102, v40, v41
	v_mul_f32_e32 v41, 0x3d372713, v40
	v_mul_f32_e32 v41, v40, v41
	v_fma_f32 v41, v40, v41, v40
	v_mul_f32_e32 v41, 0x3f4c422a, v41
	v_add_f32_e32 v41, v41, v41
	v_mul_f32_e32 v41, 0x3fb8aa3b, v41
	v_exp_f32_e32 v41, v41
	v_mul_f32_e32 v40, 0.5, v40
	v_add_f32_e32 v41, 1.0, v41
	v_rcp_f32_e32 v41, v41
	s_nop 0
	v_fma_f32 v41, v41, -2.0, 1.0
	v_add_f32_e32 v41, 1.0, v41
	v_mul_f32_e32 v40, v40, v41
	v_cvt_pk_bf16_f32 v103, v40, s0
	v_or_b32_e32 v40, s9, v84
	v_or_b32_e32 v76, s4, v40
	v_lshlrev_b64 v[40:41], 10, v[76:77]
	v_lshl_add_u64 v[40:41], v[72:73], 0, v[40:41]
	global_store_short v[40:41], v103, off
	ds_read_b32 v40, v87
	s_waitcnt lgkmcnt(0)
	v_fma_f32 v40, v102, v40, v42
	v_mul_f32_e32 v41, 0x3d372713, v40
	v_mul_f32_e32 v41, v40, v41
	v_fma_f32 v41, v40, v41, v40
	v_mul_f32_e32 v41, 0x3f4c422a, v41
	v_add_f32_e32 v41, v41, v41
	v_mul_f32_e32 v41, 0x3fb8aa3b, v41
	v_exp_f32_e32 v41, v41
	v_mul_f32_e32 v40, 0.5, v40
	v_add_f32_e32 v41, 1.0, v41
	v_rcp_f32_e32 v41, v41
	s_nop 0
	v_fma_f32 v41, v41, -2.0, 1.0
	v_add_f32_e32 v41, 1.0, v41
	v_mul_f32_e32 v40, v40, v41
	v_cvt_pk_bf16_f32 v42, v40, s0
	v_or_b32_e32 v40, s9, v86
	v_or_b32_e32 v76, s4, v40
	v_lshlrev_b64 v[40:41], 10, v[76:77]
	v_lshl_add_u64 v[40:41], v[72:73], 0, v[40:41]
	global_store_short v[40:41], v42, off
	ds_read_b32 v40, v89
	s_waitcnt lgkmcnt(0)
; __device__ __forceinline__ float ozero() { float z = 0.f; asm volatile("" : "+v"(z)); return z; }
; __device__ __forceinline__ bf f2bf(float f) { return (bf)(pk2(f, 0.f) & 0xFFFFu); }
; __device__ __forceinline__ f32x4 mfma16(bf16x8 a, bf16x8 b, f32x4 c) { return __builtin_amdgcn_mfma_f32_16x16x32_bf16(a, b, c, 0, 0, 0); }
; __device__ __forceinline__ void s5_pass2(const Params& p, int layer, int task, char* sm) {
;     ...
; #pragma unroll
;       for (int mb = 0; mb < 2; mb++) {
;         const float z_ = ozero(); f32x4 acc = {z_, z_, z_, z_};
; #pragma unroll
;         for (int ks = 0; ks < 4; ks++) {
;           bf16x8 af = *(const bf16x8*)(sS + (16 * mb + (lane & 15)) * 136 + ks * 32 + 8 * (lane >> 4));
;           acc = mfma16(af, cf[ks], acc);
;         }
; #pragma unroll
;         for (int r = 0; r < 4; r++) {
;           const int l = 16 * mb + 4 * (lane >> 4) + r;
;           float y = acc[r] + dsk * sU[l * 16 + (lane & 15)];
;           p.YG[(tok0 + sub * 32 + l) * 512 + g * 16 + (lane & 15)] = f2bf(geluf_(y));
;         }
;       }
;     }
	v_fmac_f32_e32 v43, v102, v40
	v_mul_f32_e32 v40, 0x3d372713, v43
	v_mul_f32_e32 v40, v43, v40
	v_fma_f32 v40, v43, v40, v43
	v_mul_f32_e32 v40, 0x3f4c422a, v40
	v_add_f32_e32 v40, v40, v40
	v_mul_f32_e32 v40, 0x3fb8aa3b, v40
	v_exp_f32_e32 v40, v40
	v_mul_f32_e32 v41, 0.5, v43
	v_add_f32_e32 v40, 1.0, v40
	v_rcp_f32_e32 v40, v40
	s_nop 0
	v_fma_f32 v40, v40, -2.0, 1.0
	v_add_f32_e32 v40, 1.0, v40
	v_mul_f32_e32 v40, v41, v40
	v_cvt_pk_bf16_f32 v42, v40, s0
	v_or_b32_e32 v40, s9, v88
	v_or_b32_e32 v76, s4, v40
	v_lshlrev_b64 v[40:41], 10, v[76:77]
	v_lshl_add_u64 v[40:41], v[72:73], 0, v[40:41]
	global_store_short v[40:41], v42, off
	v_mov_b32_e32 v40, v145
	ds_read_b128 v[104:107], v100 offset:6400
	ds_read_b32 v76, v91
	v_mov_b32_e32 v41, v40
	v_mov_b32_e32 v42, v40
	v_mov_b32_e32 v43, v40
	s_waitcnt lgkmcnt(1)
	s_nop 0
	v_mfma_f32_16x16x32_bf16 v[40:43], v[104:107], v[24:27], v[40:43]
	ds_read_b128 v[104:107], v100 offset:6464
	s_waitcnt lgkmcnt(0)
	v_mfma_f32_16x16x32_bf16 v[40:43], v[104:107], v[28:31], v[40:43]
	ds_read_b128 v[104:107], v100 offset:6528
	s_waitcnt lgkmcnt(0)
	v_mfma_f32_16x16x32_bf16 v[40:43], v[104:107], v[32:35], v[40:43]
	ds_read_b128 v[104:107], v100 offset:6592
	s_waitcnt lgkmcnt(0)
	v_mfma_f32_16x16x32_bf16 v[40:43], v[104:107], v[36:39], v[40:43]
	s_nop 7
	v_fma_f32 v40, v102, v76, v40
	v_mul_f32_e32 v76, 0x3d372713, v40
	v_mul_f32_e32 v76, v40, v76
	v_fma_f32 v76, v40, v76, v40
	v_mul_f32_e32 v76, 0x3f4c422a, v76
	v_add_f32_e32 v76, v76, v76
	v_mul_f32_e32 v76, 0x3fb8aa3b, v76
	v_exp_f32_e32 v76, v76
	v_mul_f32_e32 v40, 0.5, v40
	v_add_f32_e32 v76, 1.0, v76
	v_rcp_f32_e32 v76, v76
	s_nop 0
	v_fma_f32 v76, v76, -2.0, 1.0
	v_add_f32_e32 v76, 1.0, v76
	v_mul_f32_e32 v40, v40, v76
	v_or_b32_e32 v76, s9, v90
	v_or_b32_e32 v76, s4, v76
	v_lshlrev_b64 v[104:105], 10, v[76:77]
	v_cvt_pk_bf16_f32 v40, v40, s0
	v_lshl_add_u64 v[104:105], v[72:73], 0, v[104:105]
	global_store_short v[104:105], v40, off
	ds_read_b32 v40, v93
	s_waitcnt lgkmcnt(0)
	v_fma_f32 v40, v102, v40, v41
	v_mul_f32_e32 v41, 0x3d372713, v40
	v_mul_f32_e32 v41, v40, v41
	v_fma_f32 v41, v40, v41, v40
	v_mul_f32_e32 v41, 0x3f4c422a, v41
	v_add_f32_e32 v41, v41, v41
	v_mul_f32_e32 v41, 0x3fb8aa3b, v41
	v_exp_f32_e32 v41, v41
	v_mul_f32_e32 v40, 0.5, v40
	v_add_f32_e32 v41, 1.0, v41
	v_rcp_f32_e32 v41, v41
	s_nop 0
	v_fma_f32 v41, v41, -2.0, 1.0
	v_add_f32_e32 v41, 1.0, v41
	v_mul_f32_e32 v40, v40, v41
	v_cvt_pk_bf16_f32 v103, v40, s0
	v_or_b32_e32 v40, s9, v92
	v_or_b32_e32 v76, s4, v40
	v_lshlrev_b64 v[40:41], 10, v[76:77]
	v_lshl_add_u64 v[40:41], v[72:73], 0, v[40:41]
	global_store_short v[40:41], v103, off
	ds_read_b32 v40, v95
	s_waitcnt lgkmcnt(0)
	v_fma_f32 v40, v102, v40, v42
	v_mul_f32_e32 v41, 0x3d372713, v40
	v_mul_f32_e32 v41, v40, v41
	v_fma_f32 v41, v40, v41, v40
	v_mul_f32_e32 v41, 0x3f4c422a, v41
	v_add_f32_e32 v41, v41, v41
	v_mul_f32_e32 v41, 0x3fb8aa3b, v41
	v_exp_f32_e32 v41, v41
	v_mul_f32_e32 v40, 0.5, v40
	v_add_f32_e32 v41, 1.0, v41
	v_rcp_f32_e32 v41, v41
	s_nop 0
	v_fma_f32 v41, v41, -2.0, 1.0
	v_add_f32_e32 v41, 1.0, v41
	v_mul_f32_e32 v40, v40, v41
	v_cvt_pk_bf16_f32 v42, v40, s0
	v_or_b32_e32 v40, s9, v94
	v_or_b32_e32 v76, s4, v40
	v_lshlrev_b64 v[40:41], 10, v[76:77]
	v_lshl_add_u64 v[40:41], v[72:73], 0, v[40:41]
	global_store_short v[40:41], v42, off
	ds_read_b32 v40, v97
	s_waitcnt lgkmcnt(0)
	v_fmac_f32_e32 v43, v102, v40
	v_mul_f32_e32 v40, 0x3d372713, v43
	v_mul_f32_e32 v40, v43, v40
	v_fma_f32 v40, v43, v40, v43
	v_mul_f32_e32 v40, 0x3f4c422a, v40
	v_add_f32_e32 v40, v40, v40
	v_mul_f32_e32 v40, 0x3fb8aa3b, v40
	v_exp_f32_e32 v40, v40
	v_mul_f32_e32 v41, 0.5, v43
	v_add_f32_e32 v40, 1.0, v40
	v_rcp_f32_e32 v40, v40
	s_nop 0
	v_fma_f32 v40, v40, -2.0, 1.0
	v_add_f32_e32 v40, 1.0, v40
	v_mul_f32_e32 v40, v41, v40
	v_cvt_pk_bf16_f32 v42, v40, s0
	v_or_b32_e32 v40, s9, v96
	v_or_b32_e32 v76, s4, v40
	v_lshlrev_b64 v[40:41], 10, v[76:77]
	v_lshl_add_u64 v[40:41], v[72:73], 0, v[40:41]
	global_store_short v[40:41], v42, off
	s_cbranch_scc1 .LBB0_1789
	s_mov_b32 s11, s8
	s_branch .LBB0_1791

; __device__ __forceinline__ bf f2bf(float f) { return (bf)(pk2(f, 0.f) & 0xFFFFu); }
; __device__ __forceinline__ void s5_pass2(const Params& p, int layer, int task, char* sm) {
;     ...
;     for (int sub = 0; sub < 4; sub++) {
;       __builtin_amdgcn_wave_barrier();
;       if (lane < 32) s5_st_u(sU + lane * 16, ua, ub);
;       {
;         const int nsub = (sub + 1) & 3; const int ng = g + (sub == 3 ? 1 : 0);
;         if (sub < 3 || gi < 7) s5_ld_u(p, tok0 + nsub * 32 + (lane & 31), ng, ua, ub);
;       }
;       __builtin_amdgcn_wave_barrier();
;       for (int l = 0; l < 32; l++) {
;         S5_STEP(sU + l * 16)
;         sS[l * 136 + lane] = f2bf(sr); sS[l * 136 + 64 + lane] = f2bf(si);
;       }
.LBB0_2060:
	v_add_u32_e32 v103, v79, v40
	v_and_b32_e32 v43, 31, v202
	v_lshrrev_b32_e32 v42, 5, v202
	v_lshlrev_b32_e32 v43, 6, v43
	v_lshl_add_u32 v43, v42, 2, v43
	v_add_u32_e32 v43, v79, v43
	ds_read2_b32 v[170:171], v43 offset0:0 offset1:2
	ds_read2_b32 v[172:173], v43 offset0:4 offset1:6
	ds_read2_b32 v[174:175], v43 offset0:8 offset1:10
	ds_read2_b32 v[176:177], v43 offset0:12 offset1:14
	s_waitcnt lgkmcnt(0)
	s_setprio 1
	v_mfma_f32_32x32x2_f32 v[104:119], v170, v52, 0
	v_mfma_f32_32x32x2_f32 v[120:135], v170, v53, 0
	v_mfma_f32_32x32x2_f32 v[152:167], v170, v20, 0
	v_mfma_f32_32x32x2_f32 v[136:151], v170, v21, 0
	v_mfma_f32_32x32x2_f32 v[104:119], v171, v54, v[104:119]
	v_mfma_f32_32x32x2_f32 v[120:135], v171, v55, v[120:135]
	v_mfma_f32_32x32x2_f32 v[152:167], v171, v22, v[152:167]
	v_mfma_f32_32x32x2_f32 v[136:151], v171, v23, v[136:151]
	v_mfma_f32_32x32x2_f32 v[104:119], v172, v56, v[104:119]
	v_mfma_f32_32x32x2_f32 v[120:135], v172, v57, v[120:135]
	v_mfma_f32_32x32x2_f32 v[152:167], v172, v16, v[152:167]
	v_mfma_f32_32x32x2_f32 v[136:151], v172, v17, v[136:151]
	v_mfma_f32_32x32x2_f32 v[104:119], v173, v58, v[104:119]
	v_mfma_f32_32x32x2_f32 v[120:135], v173, v59, v[120:135]
	v_mfma_f32_32x32x2_f32 v[152:167], v173, v18, v[152:167]
	v_mfma_f32_32x32x2_f32 v[136:151], v173, v19, v[136:151]
	v_mfma_f32_32x32x2_f32 v[104:119], v174, v60, v[104:119]
	v_mfma_f32_32x32x2_f32 v[120:135], v174, v61, v[120:135]
	v_mfma_f32_32x32x2_f32 v[152:167], v174, v12, v[152:167]
	v_mfma_f32_32x32x2_f32 v[136:151], v174, v13, v[136:151]
	v_mfma_f32_32x32x2_f32 v[104:119], v175, v62, v[104:119]
	v_mfma_f32_32x32x2_f32 v[120:135], v175, v63, v[120:135]
	v_mfma_f32_32x32x2_f32 v[152:167], v175, v14, v[152:167]
	v_mfma_f32_32x32x2_f32 v[136:151], v175, v15, v[136:151]
	v_mfma_f32_32x32x2_f32 v[104:119], v176, v64, v[104:119]
	v_mfma_f32_32x32x2_f32 v[120:135], v176, v65, v[120:135]
	v_mfma_f32_32x32x2_f32 v[152:167], v176, v8, v[152:167]
	v_mfma_f32_32x32x2_f32 v[136:151], v176, v9, v[136:151]
	v_mfma_f32_32x32x2_f32 v[104:119], v177, v66, v[104:119]
	v_mfma_f32_32x32x2_f32 v[120:135], v177, v67, v[120:135]
	v_mfma_f32_32x32x2_f32 v[152:167], v177, v10, v[152:167]
	v_mfma_f32_32x32x2_f32 v[136:151], v177, v11, v[136:151]
	s_setprio 0
	s_nop 7
	s_nop 7
	s_nop 7
	v_permlane32_swap_b32_e32 v104, v152
	v_permlane32_swap_b32_e32 v120, v136
	v_permlane32_swap_b32_e32 v105, v153
	v_permlane32_swap_b32_e32 v121, v137
	v_permlane32_swap_b32_e32 v106, v154
	v_permlane32_swap_b32_e32 v122, v138
	v_permlane32_swap_b32_e32 v107, v155
	v_permlane32_swap_b32_e32 v123, v139
	v_permlane32_swap_b32_e32 v108, v156
	v_permlane32_swap_b32_e32 v124, v140
	v_permlane32_swap_b32_e32 v109, v157
	v_permlane32_swap_b32_e32 v125, v141
	v_permlane32_swap_b32_e32 v110, v158
	v_permlane32_swap_b32_e32 v126, v142
	v_permlane32_swap_b32_e32 v111, v159
	v_permlane32_swap_b32_e32 v127, v143
	v_permlane32_swap_b32_e32 v112, v160
	v_permlane32_swap_b32_e32 v128, v144
	v_permlane32_swap_b32_e32 v113, v161
	v_permlane32_swap_b32_e32 v129, v145
	v_permlane32_swap_b32_e32 v114, v162
	v_permlane32_swap_b32_e32 v130, v146
	v_permlane32_swap_b32_e32 v115, v163
	v_permlane32_swap_b32_e32 v131, v147
	v_permlane32_swap_b32_e32 v116, v164
	v_permlane32_swap_b32_e32 v132, v148
	v_permlane32_swap_b32_e32 v117, v165
	v_permlane32_swap_b32_e32 v133, v149
	v_permlane32_swap_b32_e32 v118, v166
	v_permlane32_swap_b32_e32 v134, v150
	v_permlane32_swap_b32_e32 v119, v167
	v_permlane32_swap_b32_e32 v135, v151
	s_waitcnt vmcnt(5)
	v_mul_f32_e32 v76, v74, v71
	v_mul_f32_e32 v77, v75, v71
	v_fma_f32 v40, v68, v70, -v76
	v_fma_f32 v41, v69, v70, v77
	v_add_f32_e32 v70, v40, v104
	v_add_f32_e32 v71, v41, v120
	v_mul_f32_e32 v76, v74, v71
	v_mul_f32_e32 v77, v75, v71
	v_cvt_pk_bf16_f32 v42, v70, v71
	v_fma_f32 v40, v68, v70, -v76
	v_fma_f32 v41, v69, v70, v77
	ds_write_b16 v103, v42
	v_add_f32_e32 v70, v40, v105
	v_add_f32_e32 v71, v41, v121
	ds_write_b16_d16_hi v103, v42 offset:128
	v_mul_f32_e32 v76, v74, v71
	v_mul_f32_e32 v77, v75, v71
	v_cvt_pk_bf16_f32 v42, v70, v71
	v_fma_f32 v40, v68, v70, -v76
	v_fma_f32 v41, v69, v70, v77
	ds_write_b16 v103, v42 offset:272
	v_add_f32_e32 v70, v40, v106
	v_add_f32_e32 v71, v41, v122
	ds_write_b16_d16_hi v103, v42 offset:400
	v_mul_f32_e32 v76, v74, v71
	v_mul_f32_e32 v77, v75, v71
	v_cvt_pk_bf16_f32 v42, v70, v71
	v_fma_f32 v40, v68, v70, -v76
	v_fma_f32 v41, v69, v70, v77
	ds_write_b16 v103, v42 offset:544
	v_add_f32_e32 v70, v40, v107
	v_add_f32_e32 v71, v41, v123
	ds_write_b16_d16_hi v103, v42 offset:672
	v_mul_f32_e32 v76, v74, v71
	v_mul_f32_e32 v77, v75, v71
	v_cvt_pk_bf16_f32 v42, v70, v71
	v_fma_f32 v40, v68, v70, -v76
	v_fma_f32 v41, v69, v70, v77
	ds_write_b16 v103, v42 offset:816
	v_add_f32_e32 v70, v40, v152
	v_add_f32_e32 v71, v41, v136
	ds_write_b16_d16_hi v103, v42 offset:944
	v_mul_f32_e32 v76, v74, v71
	v_mul_f32_e32 v77, v75, v71
	v_cvt_pk_bf16_f32 v42, v70, v71
	v_fma_f32 v40, v68, v70, -v76
	v_fma_f32 v41, v69, v70, v77
	ds_write_b16 v103, v42 offset:1088
	v_add_f32_e32 v70, v40, v153
	v_add_f32_e32 v71, v41, v137
	ds_write_b16_d16_hi v103, v42 offset:1216
	v_mul_f32_e32 v76, v74, v71
	v_mul_f32_e32 v77, v75, v71
	v_cvt_pk_bf16_f32 v42, v70, v71
	v_fma_f32 v40, v68, v70, -v76
	v_fma_f32 v41, v69, v70, v77
	ds_write_b16 v103, v42 offset:1360
	v_add_f32_e32 v70, v40, v154
	v_add_f32_e32 v71, v41, v138
	ds_write_b16_d16_hi v103, v42 offset:1488
	v_mul_f32_e32 v76, v74, v71
	v_mul_f32_e32 v77, v75, v71
	v_cvt_pk_bf16_f32 v42, v70, v71
	v_fma_f32 v40, v68, v70, -v76
	v_fma_f32 v41, v69, v70, v77
	ds_write_b16 v103, v42 offset:1632
	v_add_f32_e32 v70, v40, v155
; __device__ __forceinline__ bf f2bf(float f) { return (bf)(pk2(f, 0.f) & 0xFFFFu); }
; __device__ __forceinline__ void s5_pass2(const Params& p, int layer, int task, char* sm) {
;     ...
;       for (int l = 0; l < 32; l++) {
;         S5_STEP(sU + l * 16)
;         sS[l * 136 + lane] = f2bf(sr); sS[l * 136 + 64 + lane] = f2bf(si);
;       }
	v_add_f32_e32 v71, v41, v139
	ds_write_b16_d16_hi v103, v42 offset:1760
	v_mul_f32_e32 v76, v74, v71
	v_mul_f32_e32 v77, v75, v71
	v_cvt_pk_bf16_f32 v42, v70, v71
	v_fma_f32 v40, v68, v70, -v76
	v_fma_f32 v41, v69, v70, v77
	ds_write_b16 v103, v42 offset:1904
	v_add_f32_e32 v70, v40, v108
	v_add_f32_e32 v71, v41, v124
	ds_write_b16_d16_hi v103, v42 offset:2032
	v_mul_f32_e32 v76, v74, v71
	v_mul_f32_e32 v77, v75, v71
	v_cvt_pk_bf16_f32 v42, v70, v71
	v_fma_f32 v40, v68, v70, -v76
	v_fma_f32 v41, v69, v70, v77
	ds_write_b16 v103, v42 offset:2176
	v_add_f32_e32 v70, v40, v109
	v_add_f32_e32 v71, v41, v125
	ds_write_b16_d16_hi v103, v42 offset:2304
	v_mul_f32_e32 v76, v74, v71
	v_mul_f32_e32 v77, v75, v71
	v_cvt_pk_bf16_f32 v42, v70, v71
	v_fma_f32 v40, v68, v70, -v76
	v_fma_f32 v41, v69, v70, v77
	ds_write_b16 v103, v42 offset:2448
	v_add_f32_e32 v70, v40, v110
	v_add_f32_e32 v71, v41, v126
	ds_write_b16_d16_hi v103, v42 offset:2576
	v_mul_f32_e32 v76, v74, v71
	v_mul_f32_e32 v77, v75, v71
	v_cvt_pk_bf16_f32 v42, v70, v71
	v_fma_f32 v40, v68, v70, -v76
	v_fma_f32 v41, v69, v70, v77
	ds_write_b16 v103, v42 offset:2720
	v_add_f32_e32 v70, v40, v111
	v_add_f32_e32 v71, v41, v127
	ds_write_b16_d16_hi v103, v42 offset:2848
	v_mul_f32_e32 v76, v74, v71
	v_mul_f32_e32 v77, v75, v71
	v_cvt_pk_bf16_f32 v42, v70, v71
	v_fma_f32 v40, v68, v70, -v76
	v_fma_f32 v41, v69, v70, v77
	ds_write_b16 v103, v42 offset:2992
	v_add_f32_e32 v70, v40, v156
	v_add_f32_e32 v71, v41, v140
	ds_write_b16_d16_hi v103, v42 offset:3120
	v_mul_f32_e32 v76, v74, v71
	v_mul_f32_e32 v77, v75, v71
	v_cvt_pk_bf16_f32 v42, v70, v71
	v_fma_f32 v40, v68, v70, -v76
	v_fma_f32 v41, v69, v70, v77
	ds_write_b16 v103, v42 offset:3264
	v_add_f32_e32 v70, v40, v157
	v_add_f32_e32 v71, v41, v141
	ds_write_b16_d16_hi v103, v42 offset:3392
	v_mul_f32_e32 v76, v74, v71
	v_mul_f32_e32 v77, v75, v71
	v_cvt_pk_bf16_f32 v42, v70, v71
	v_fma_f32 v40, v68, v70, -v76
	v_fma_f32 v41, v69, v70, v77
	ds_write_b16 v103, v42 offset:3536
	v_add_f32_e32 v70, v40, v158
	v_add_f32_e32 v71, v41, v142
	ds_write_b16_d16_hi v103, v42 offset:3664
	v_mul_f32_e32 v76, v74, v71
	v_mul_f32_e32 v77, v75, v71
	v_cvt_pk_bf16_f32 v42, v70, v71
	v_fma_f32 v40, v68, v70, -v76
	v_fma_f32 v41, v69, v70, v77
	ds_write_b16 v103, v42 offset:3808
	v_add_f32_e32 v70, v40, v159
	v_add_f32_e32 v71, v41, v143
	ds_write_b16_d16_hi v103, v42 offset:3936
	v_mul_f32_e32 v76, v74, v71
	v_mul_f32_e32 v77, v75, v71
	v_cvt_pk_bf16_f32 v42, v70, v71
	v_fma_f32 v40, v68, v70, -v76
	v_fma_f32 v41, v69, v70, v77
	ds_write_b16 v103, v42 offset:4080
	v_add_f32_e32 v70, v40, v112
	v_add_f32_e32 v71, v41, v128
	ds_write_b16_d16_hi v103, v42 offset:4208
	v_mul_f32_e32 v76, v74, v71
	v_mul_f32_e32 v77, v75, v71
	v_cvt_pk_bf16_f32 v42, v70, v71
	v_fma_f32 v40, v68, v70, -v76
	v_fma_f32 v41, v69, v70, v77
	ds_write_b16 v103, v42 offset:4352
	v_add_f32_e32 v70, v40, v113
	v_add_f32_e32 v71, v41, v129
	ds_write_b16_d16_hi v103, v42 offset:4480
	v_mul_f32_e32 v76, v74, v71
	v_mul_f32_e32 v77, v75, v71
	v_cvt_pk_bf16_f32 v42, v70, v71
	v_fma_f32 v40, v68, v70, -v76
	v_fma_f32 v41, v69, v70, v77
	ds_write_b16 v103, v42 offset:4624
	v_add_f32_e32 v70, v40, v114
	v_add_f32_e32 v71, v41, v130
	ds_write_b16_d16_hi v103, v42 offset:4752
	v_mul_f32_e32 v76, v74, v71
	v_mul_f32_e32 v77, v75, v71
	v_cvt_pk_bf16_f32 v42, v70, v71
	v_fma_f32 v40, v68, v70, -v76
	v_fma_f32 v41, v69, v70, v77
	ds_write_b16 v103, v42 offset:4896
	v_add_f32_e32 v70, v40, v115
	v_add_f32_e32 v71, v41, v131
	ds_write_b16_d16_hi v103, v42 offset:5024
	v_mul_f32_e32 v76, v74, v71
	v_mul_f32_e32 v77, v75, v71
	v_cvt_pk_bf16_f32 v42, v70, v71
	v_fma_f32 v40, v68, v70, -v76
	v_fma_f32 v41, v69, v70, v77
	ds_write_b16 v103, v42 offset:5168
	v_add_f32_e32 v70, v40, v160
	v_add_f32_e32 v71, v41, v144
	ds_write_b16_d16_hi v103, v42 offset:5296
	v_mul_f32_e32 v76, v74, v71
	v_mul_f32_e32 v77, v75, v71
	v_cvt_pk_bf16_f32 v42, v70, v71
	v_fma_f32 v40, v68, v70, -v76
	v_fma_f32 v41, v69, v70, v77
	ds_write_b16 v103, v42 offset:5440
	v_add_f32_e32 v70, v40, v161
	v_add_f32_e32 v71, v41, v145
	ds_write_b16_d16_hi v103, v42 offset:5568
	v_mul_f32_e32 v76, v74, v71
	v_mul_f32_e32 v77, v75, v71
	v_cvt_pk_bf16_f32 v42, v70, v71
	v_fma_f32 v40, v68, v70, -v76
	v_fma_f32 v41, v69, v70, v77
	ds_write_b16 v103, v42 offset:5712
	v_add_f32_e32 v70, v40, v162
	v_add_f32_e32 v71, v41, v146
	ds_write_b16_d16_hi v103, v42 offset:5840
	v_mul_f32_e32 v76, v74, v71
	v_mul_f32_e32 v77, v75, v71
	v_cvt_pk_bf16_f32 v42, v70, v71
	v_fma_f32 v40, v68, v70, -v76
	v_fma_f32 v41, v69, v70, v77
	ds_write_b16 v103, v42 offset:5984
	v_add_f32_e32 v70, v40, v163
	v_add_f32_e32 v71, v41, v147
	ds_write_b16_d16_hi v103, v42 offset:6112
	v_mul_f32_e32 v76, v74, v71
	v_mul_f32_e32 v77, v75, v71
	v_cvt_pk_bf16_f32 v42, v70, v71
	v_fma_f32 v40, v68, v70, -v76
	v_fma_f32 v41, v69, v70, v77
	ds_write_b16 v103, v42 offset:6256
	v_add_f32_e32 v70, v40, v116
	v_add_f32_e32 v71, v41, v132
	ds_write_b16_d16_hi v103, v42 offset:6384
	v_mul_f32_e32 v76, v74, v71
	v_mul_f32_e32 v77, v75, v71
	v_cvt_pk_bf16_f32 v42, v70, v71
	v_fma_f32 v40, v68, v70, -v76
	v_fma_f32 v41, v69, v70, v77
	ds_write_b16 v103, v42 offset:6528
	v_add_f32_e32 v70, v40, v117
	v_add_f32_e32 v71, v41, v133
	ds_write_b16_d16_hi v103, v42 offset:6656
	v_mul_f32_e32 v76, v74, v71
	v_mul_f32_e32 v77, v75, v71
	v_cvt_pk_bf16_f32 v42, v70, v71
	v_fma_f32 v40, v68, v70, -v76
	v_fma_f32 v41, v69, v70, v77
	ds_write_b16 v103, v42 offset:6800
	v_add_f32_e32 v70, v40, v118
	v_add_f32_e32 v71, v41, v134
	ds_write_b16_d16_hi v103, v42 offset:6928
	v_mul_f32_e32 v76, v74, v71
; __device__ __forceinline__ float ozero() { float z = 0.f; asm volatile("" : "+v"(z)); return z; }
; __device__ __forceinline__ bf f2bf(float f) { return (bf)(pk2(f, 0.f) & 0xFFFFu); }
; __device__ __forceinline__ f32x4 mfma16(bf16x8 a, bf16x8 b, f32x4 c) { return __builtin_amdgcn_mfma_f32_16x16x32_bf16(a, b, c, 0, 0, 0); }
; __device__ __forceinline__ void s5_pass2(const Params& p, int layer, int task, char* sm) {
;     ...
;         sS[l * 136 + lane] = f2bf(sr); sS[l * 136 + 64 + lane] = f2bf(si);
;       }
;       __builtin_amdgcn_wave_barrier();
; #pragma unroll
;       for (int mb = 0; mb < 2; mb++) {
;         const float z_ = ozero(); f32x4 acc = {z_, z_, z_, z_};
; #pragma unroll
;         for (int ks = 0; ks < 4; ks++) {
;           bf16x8 af = *(const bf16x8*)(sS + (16 * mb + (lane & 15)) * 136 + ks * 32 + 8 * (lane >> 4));
;           acc = mfma16(af, cf[ks], acc);
;         }
; #pragma unroll
;         for (int r = 0; r < 4; r++) {
;           const int l = 16 * mb + 4 * (lane >> 4) + r;
;           float y = acc[r] + dsk * sU[l * 16 + (lane & 15)];
;           p.YG[(tok0 + sub * 32 + l) * 512 + g * 16 + (lane & 15)] = f2bf(geluf_(y));
	v_mul_f32_e32 v77, v75, v71
	v_cvt_pk_bf16_f32 v42, v70, v71
	v_fma_f32 v40, v68, v70, -v76
	v_fma_f32 v41, v69, v70, v77
	ds_write_b16 v103, v42 offset:7072
	v_add_f32_e32 v70, v40, v119
	v_add_f32_e32 v71, v41, v135
	ds_write_b16_d16_hi v103, v42 offset:7200
	v_mul_f32_e32 v76, v74, v71
	v_mul_f32_e32 v77, v75, v71
	v_cvt_pk_bf16_f32 v42, v70, v71
	v_fma_f32 v40, v68, v70, -v76
	v_fma_f32 v41, v69, v70, v77
	ds_write_b16 v103, v42 offset:7344
	v_add_f32_e32 v70, v40, v164
	v_add_f32_e32 v71, v41, v148
	ds_write_b16_d16_hi v103, v42 offset:7472
	v_mul_f32_e32 v76, v74, v71
	v_mul_f32_e32 v77, v75, v71
	v_cvt_pk_bf16_f32 v42, v70, v71
	v_fma_f32 v40, v68, v70, -v76
	v_fma_f32 v41, v69, v70, v77
	ds_write_b16 v103, v42 offset:7616
	v_add_f32_e32 v70, v40, v165
	v_add_f32_e32 v71, v41, v149
	ds_write_b16_d16_hi v103, v42 offset:7744
	v_mul_f32_e32 v76, v74, v71
	v_mul_f32_e32 v77, v75, v71
	v_cvt_pk_bf16_f32 v42, v70, v71
	v_fma_f32 v40, v68, v70, -v76
	v_fma_f32 v41, v69, v70, v77
	ds_write_b16 v103, v42 offset:7888
	v_add_f32_e32 v70, v40, v166
	v_add_f32_e32 v71, v41, v150
	ds_write_b16_d16_hi v103, v42 offset:8016
	v_mul_f32_e32 v76, v74, v71
	v_mul_f32_e32 v77, v75, v71
	v_cvt_pk_bf16_f32 v42, v70, v71
	v_fma_f32 v40, v68, v70, -v76
	v_fma_f32 v41, v69, v70, v77
	ds_write_b16 v103, v42 offset:8160
	v_add_f32_e32 v70, v40, v167
	v_add_f32_e32 v71, v41, v151
	ds_write_b16_d16_hi v103, v42 offset:8288
	v_cvt_pk_bf16_f32 v42, v70, v71
	ds_write_b16 v103, v42 offset:8432
	ds_write_b16_d16_hi v103, v42 offset:8560
	s_waitcnt lgkmcnt(0)
	v_mov_b32_e32 v145, 0
	v_mov_b32_e32 v40, v145
	ds_read_b128 v[104:107], v100 offset:2048
	ds_read_b32 v76, v83
	v_mov_b32_e32 v41, v40
	v_mov_b32_e32 v42, v40
	v_mov_b32_e32 v43, v40
	s_lshl_b32 s9, s12, 5
	v_mov_b32_e32 v77, s5
	s_cmp_eq_u32 s8, 4
	s_waitcnt vmcnt(4) lgkmcnt(1)
	v_mfma_f32_16x16x32_bf16 v[40:43], v[104:107], v[24:27], v[40:43]
	ds_read_b128 v[104:107], v100 offset:2112
	s_waitcnt vmcnt(3) lgkmcnt(0)
	v_mfma_f32_16x16x32_bf16 v[40:43], v[104:107], v[28:31], v[40:43]
	ds_read_b128 v[104:107], v100 offset:2176
	s_waitcnt vmcnt(2) lgkmcnt(0)
	v_mfma_f32_16x16x32_bf16 v[40:43], v[104:107], v[32:35], v[40:43]
	ds_read_b128 v[104:107], v100 offset:2240
	s_waitcnt vmcnt(1) lgkmcnt(0)
	v_mfma_f32_16x16x32_bf16 v[40:43], v[104:107], v[36:39], v[40:43]
	s_waitcnt vmcnt(0)
	s_nop 6
	v_fma_f32 v40, v102, v76, v40
	v_mul_f32_e32 v76, 0x3d372713, v40
	v_mul_f32_e32 v76, v40, v76
	v_fma_f32 v76, v40, v76, v40
	v_mul_f32_e32 v76, 0x3f4c422a, v76
	v_add_f32_e32 v76, v76, v76
	v_mul_f32_e32 v76, 0x3fb8aa3b, v76
	v_exp_f32_e32 v76, v76
	v_mul_f32_e32 v40, 0.5, v40
	v_add_f32_e32 v76, 1.0, v76
	v_rcp_f32_e32 v76, v76
	s_nop 0
	v_fma_f32 v76, v76, -2.0, 1.0
	v_add_f32_e32 v76, 1.0, v76
	v_mul_f32_e32 v40, v40, v76
	v_or_b32_e32 v76, s9, v82
	v_or_b32_e32 v76, s4, v76
	v_lshlrev_b64 v[104:105], 10, v[76:77]
	v_cvt_pk_bf16_f32 v40, v40, s0
	v_lshl_add_u64 v[104:105], v[72:73], 0, v[104:105]
	global_store_short v[104:105], v40, off
	ds_read_b32 v40, v85
	s_waitcnt lgkmcnt(0)
	v_fma_f32 v40, v102, v40, v41
	v_mul_f32_e32 v41, 0x3d372713, v40
	v_mul_f32_e32 v41, v40, v41
	v_fma_f32 v41, v40, v41, v40
	v_mul_f32_e32 v41, 0x3f4c422a, v41
	v_add_f32_e32 v41, v41, v41
	v_mul_f32_e32 v41, 0x3fb8aa3b, v41
	v_exp_f32_e32 v41, v41
	v_mul_f32_e32 v40, 0.5, v40
	v_add_f32_e32 v41, 1.0, v41
	v_rcp_f32_e32 v41, v41
	s_nop 0
	v_fma_f32 v41, v41, -2.0, 1.0
	v_add_f32_e32 v41, 1.0, v41
	v_mul_f32_e32 v40, v40, v41
	v_cvt_pk_bf16_f32 v103, v40, s0
	v_or_b32_e32 v40, s9, v84
	v_or_b32_e32 v76, s4, v40
	v_lshlrev_b64 v[40:41], 10, v[76:77]
	v_lshl_add_u64 v[40:41], v[72:73], 0, v[40:41]
	global_store_short v[40:41], v103, off
	ds_read_b32 v40, v87
	s_waitcnt lgkmcnt(0)
	v_fma_f32 v40, v102, v40, v42
	v_mul_f32_e32 v41, 0x3d372713, v40
	v_mul_f32_e32 v41, v40, v41
	v_fma_f32 v41, v40, v41, v40
	v_mul_f32_e32 v41, 0x3f4c422a, v41
	v_add_f32_e32 v41, v41, v41
	v_mul_f32_e32 v41, 0x3fb8aa3b, v41
	v_exp_f32_e32 v41, v41
	v_mul_f32_e32 v40, 0.5, v40
	v_add_f32_e32 v41, 1.0, v41
	v_rcp_f32_e32 v41, v41
	s_nop 0
	v_fma_f32 v41, v41, -2.0, 1.0
	v_add_f32_e32 v41, 1.0, v41
	v_mul_f32_e32 v40, v40, v41
	v_cvt_pk_bf16_f32 v42, v40, s0
	v_or_b32_e32 v40, s9, v86
	v_or_b32_e32 v76, s4, v40
	v_lshlrev_b64 v[40:41], 10, v[76:77]
	v_lshl_add_u64 v[40:41], v[72:73], 0, v[40:41]
	global_store_short v[40:41], v42, off
	ds_read_b32 v40, v89
	s_waitcnt lgkmcnt(0)
; __device__ __forceinline__ float ozero() { float z = 0.f; asm volatile("" : "+v"(z)); return z; }
; __device__ __forceinline__ bf f2bf(float f) { return (bf)(pk2(f, 0.f) & 0xFFFFu); }
; __device__ __forceinline__ f32x4 mfma16(bf16x8 a, bf16x8 b, f32x4 c) { return __builtin_amdgcn_mfma_f32_16x16x32_bf16(a, b, c, 0, 0, 0); }
; __device__ __forceinline__ void s5_pass2(const Params& p, int layer, int task, char* sm) {
;     ...
;       for (int mb = 0; mb < 2; mb++) {
;         const float z_ = ozero(); f32x4 acc = {z_, z_, z_, z_};
; #pragma unroll
;         for (int ks = 0; ks < 4; ks++) {
;           bf16x8 af = *(const bf16x8*)(sS + (16 * mb + (lane & 15)) * 136 + ks * 32 + 8 * (lane >> 4));
;           acc = mfma16(af, cf[ks], acc);
;         }
; #pragma unroll
;         for (int r = 0; r < 4; r++) {
;           const int l = 16 * mb + 4 * (lane >> 4) + r;
;           float y = acc[r] + dsk * sU[l * 16 + (lane & 15)];
;           p.YG[(tok0 + sub * 32 + l) * 512 + g * 16 + (lane & 15)] = f2bf(geluf_(y));
;         }
;       }
;     }
	v_fmac_f32_e32 v43, v102, v40
	v_mul_f32_e32 v40, 0x3d372713, v43
	v_mul_f32_e32 v40, v43, v40
	v_fma_f32 v40, v43, v40, v43
	v_mul_f32_e32 v40, 0x3f4c422a, v40
	v_add_f32_e32 v40, v40, v40
	v_mul_f32_e32 v40, 0x3fb8aa3b, v40
	v_exp_f32_e32 v40, v40
	v_mul_f32_e32 v41, 0.5, v43
	v_add_f32_e32 v40, 1.0, v40
	v_rcp_f32_e32 v40, v40
	s_nop 0
	v_fma_f32 v40, v40, -2.0, 1.0
	v_add_f32_e32 v40, 1.0, v40
	v_mul_f32_e32 v40, v41, v40
	v_cvt_pk_bf16_f32 v42, v40, s0
	v_or_b32_e32 v40, s9, v88
	v_or_b32_e32 v76, s4, v40
	v_lshlrev_b64 v[40:41], 10, v[76:77]
	v_lshl_add_u64 v[40:41], v[72:73], 0, v[40:41]
	global_store_short v[40:41], v42, off
	v_mov_b32_e32 v40, v145
	ds_read_b128 v[104:107], v100 offset:6400
	ds_read_b32 v76, v91
	v_mov_b32_e32 v41, v40
	v_mov_b32_e32 v42, v40
	v_mov_b32_e32 v43, v40
	s_waitcnt lgkmcnt(1)
	s_nop 0
	v_mfma_f32_16x16x32_bf16 v[40:43], v[104:107], v[24:27], v[40:43]
	ds_read_b128 v[104:107], v100 offset:6464
	s_waitcnt lgkmcnt(0)
	v_mfma_f32_16x16x32_bf16 v[40:43], v[104:107], v[28:31], v[40:43]
	ds_read_b128 v[104:107], v100 offset:6528
	s_waitcnt lgkmcnt(0)
	v_mfma_f32_16x16x32_bf16 v[40:43], v[104:107], v[32:35], v[40:43]
	ds_read_b128 v[104:107], v100 offset:6592
	s_waitcnt lgkmcnt(0)
	v_mfma_f32_16x16x32_bf16 v[40:43], v[104:107], v[36:39], v[40:43]
	s_nop 7
	v_fma_f32 v40, v102, v76, v40
	v_mul_f32_e32 v76, 0x3d372713, v40
	v_mul_f32_e32 v76, v40, v76
	v_fma_f32 v76, v40, v76, v40
	v_mul_f32_e32 v76, 0x3f4c422a, v76
	v_add_f32_e32 v76, v76, v76
	v_mul_f32_e32 v76, 0x3fb8aa3b, v76
	v_exp_f32_e32 v76, v76
	v_mul_f32_e32 v40, 0.5, v40
	v_add_f32_e32 v76, 1.0, v76
	v_rcp_f32_e32 v76, v76
	s_nop 0
	v_fma_f32 v76, v76, -2.0, 1.0
	v_add_f32_e32 v76, 1.0, v76
	v_mul_f32_e32 v40, v40, v76
	v_or_b32_e32 v76, s9, v90
	v_or_b32_e32 v76, s4, v76
	v_lshlrev_b64 v[104:105], 10, v[76:77]
	v_cvt_pk_bf16_f32 v40, v40, s0
	v_lshl_add_u64 v[104:105], v[72:73], 0, v[104:105]
	global_store_short v[104:105], v40, off
	ds_read_b32 v40, v93
	s_waitcnt lgkmcnt(0)
	v_fma_f32 v40, v102, v40, v41
	v_mul_f32_e32 v41, 0x3d372713, v40
	v_mul_f32_e32 v41, v40, v41
	v_fma_f32 v41, v40, v41, v40
	v_mul_f32_e32 v41, 0x3f4c422a, v41
	v_add_f32_e32 v41, v41, v41
	v_mul_f32_e32 v41, 0x3fb8aa3b, v41
	v_exp_f32_e32 v41, v41
	v_mul_f32_e32 v40, 0.5, v40
	v_add_f32_e32 v41, 1.0, v41
	v_rcp_f32_e32 v41, v41
	s_nop 0
	v_fma_f32 v41, v41, -2.0, 1.0
	v_add_f32_e32 v41, 1.0, v41
	v_mul_f32_e32 v40, v40, v41
	v_cvt_pk_bf16_f32 v103, v40, s0
	v_or_b32_e32 v40, s9, v92
	v_or_b32_e32 v76, s4, v40
	v_lshlrev_b64 v[40:41], 10, v[76:77]
	v_lshl_add_u64 v[40:41], v[72:73], 0, v[40:41]
	global_store_short v[40:41], v103, off
	ds_read_b32 v40, v95
	s_waitcnt lgkmcnt(0)
	v_fma_f32 v40, v102, v40, v42
	v_mul_f32_e32 v41, 0x3d372713, v40
	v_mul_f32_e32 v41, v40, v41
	v_fma_f32 v41, v40, v41, v40
	v_mul_f32_e32 v41, 0x3f4c422a, v41
	v_add_f32_e32 v41, v41, v41
	v_mul_f32_e32 v41, 0x3fb8aa3b, v41
	v_exp_f32_e32 v41, v41
	v_mul_f32_e32 v40, 0.5, v40
	v_add_f32_e32 v41, 1.0, v41
	v_rcp_f32_e32 v41, v41
	s_nop 0
	v_fma_f32 v41, v41, -2.0, 1.0
	v_add_f32_e32 v41, 1.0, v41
	v_mul_f32_e32 v40, v40, v41
	v_cvt_pk_bf16_f32 v42, v40, s0
	v_or_b32_e32 v40, s9, v94
	v_or_b32_e32 v76, s4, v40
	v_lshlrev_b64 v[40:41], 10, v[76:77]
	v_lshl_add_u64 v[40:41], v[72:73], 0, v[40:41]
	global_store_short v[40:41], v42, off
	ds_read_b32 v40, v97
	s_waitcnt lgkmcnt(0)
	v_fmac_f32_e32 v43, v102, v40
	v_mul_f32_e32 v40, 0x3d372713, v43
	v_mul_f32_e32 v40, v43, v40
	v_fma_f32 v40, v43, v40, v43
	v_mul_f32_e32 v40, 0x3f4c422a, v40
	v_add_f32_e32 v40, v40, v40
	v_mul_f32_e32 v40, 0x3fb8aa3b, v40
	v_exp_f32_e32 v40, v40
	v_mul_f32_e32 v41, 0.5, v43
	v_add_f32_e32 v40, 1.0, v40
	v_rcp_f32_e32 v40, v40
	s_nop 0
	v_fma_f32 v40, v40, -2.0, 1.0
	v_add_f32_e32 v40, 1.0, v40
	v_mul_f32_e32 v40, v41, v40
	v_cvt_pk_bf16_f32 v42, v40, s0
	v_or_b32_e32 v40, s9, v96
	v_or_b32_e32 v76, s4, v40
	v_lshlrev_b64 v[40:41], 10, v[76:77]
	v_lshl_add_u64 v[40:41], v[72:73], 0, v[40:41]
	global_store_short v[40:41], v42, off
	s_cbranch_scc1 .LBB0_2053
	s_mov_b32 s12, s8
	s_branch .LBB0_2055
